# DMA-first reorder in FFN GEMM load segments
# speedup vs baseline: 1.0043x; 1.0043x over previous
.LBB0_174:
	s_ashr_i32 s31, s30, 31
	s_lshl_b64 s[34:35], s[30:31], 19
	s_add_u32 s34, s48, s34
	s_addc_u32 s35, s49, s35
	s_ashr_i32 s29, s28, 31
	s_lshl_b64 s[36:37], s[28:29], 19
	s_add_u32 s36, s51, s36
	s_mov_b32 s44, 0
	s_addc_u32 s37, s52, s37
	s_ashr_i32 s45, s44, 31
	s_lshl_b64 s[76:77], s[44:45], 7
	s_add_u32 s78, s76, 0x100
	s_addc_u32 s79, s77, 0
	s_add_u32 s44, s42, s78
	ds_read_b128 v[0:3], v141
	ds_read_b128 v[4:7], v141 offset:1024
	ds_read_b128 v[8:11], v141 offset:2048
	ds_read_b128 v[12:15], v141 offset:3072
	ds_read_b128 v[16:19], v142
	ds_read_b128 v[20:23], v142 offset:1024
	ds_read_b128 v[24:27], v142 offset:2048
	ds_read_b128 v[28:31], v142 offset:3072
	s_addc_u32 s45, s43, s79
	s_and_b64 s[74:75], s[4:5], exec
	s_cselect_b32 s31, s37, s41
	s_cselect_b32 s74, s36, s40
	s_add_u32 s78, s40, s78
	s_addc_u32 s79, s41, s79
	s_add_u32 s76, s42, s76
	s_mov_b32 s29, 0
	s_addc_u32 s77, s43, s77
	v_lshl_add_u64 v[64:65], s[76:77], 0, v[130:131]
	s_mov_b32 m0, s66
	v_lshl_add_u64 v[66:67], v[64:65], 0, s[22:23]
	ds_read_b128 v[32:35], v143
	ds_read_b128 v[36:39], v143 offset:1024
	ds_read_b128 v[40:43], v143 offset:2048
	ds_read_b128 v[44:47], v143 offset:3072
	ds_read_b128 v[48:51], v143 offset:4096
	ds_read_b128 v[52:55], v143 offset:5120
	ds_read_b128 v[56:59], v143 offset:6144
	ds_read_b128 v[60:63], v143 offset:7168
	global_load_lds_dwordx4 v[66:67], off
	v_lshl_add_u64 v[64:65], v[64:65], 0, s[24:25]
	s_mov_b32 m0, s67
	s_and_b64 s[76:77], s[4:5], exec
	global_load_lds_dwordx4 v[64:65], off
	s_waitcnt vmcnt(16)
	s_waitcnt lgkmcnt(0)
	s_cselect_b32 s75, s35, s43
	s_cselect_b32 s76, s34, s42
	s_barrier
	s_setprio 1
	s_waitcnt lgkmcnt(0)
	v_mfma_f32_16x16x32_bf16 v[64:67], v[0:3], v[32:35], 0
	v_mfma_f32_16x16x32_bf16 v[68:71], v[8:11], v[32:35], 0
	v_mfma_f32_16x16x32_bf16 v[72:75], v[0:3], v[40:43], 0
	v_mfma_f32_16x16x32_bf16 v[76:79], v[8:11], v[40:43], 0
	v_mfma_f32_16x16x32_bf16 v[80:83], v[0:3], v[48:51], 0
	v_mfma_f32_16x16x32_bf16 v[84:87], v[8:11], v[48:51], 0
	v_mfma_f32_16x16x32_bf16 v[88:91], v[0:3], v[56:59], 0
	v_mfma_f32_16x16x32_bf16 v[92:95], v[8:11], v[56:59], 0
	v_mfma_f32_16x16x32_bf16 v[64:67], v[4:7], v[36:39], v[64:67]
	v_mfma_f32_16x16x32_bf16 v[68:71], v[12:15], v[36:39], v[68:71]
	v_mfma_f32_16x16x32_bf16 v[72:75], v[4:7], v[44:47], v[72:75]
	v_mfma_f32_16x16x32_bf16 v[76:79], v[12:15], v[44:47], v[76:79]
	v_mfma_f32_16x16x32_bf16 v[80:83], v[4:7], v[52:55], v[80:83]
	v_mfma_f32_16x16x32_bf16 v[84:87], v[12:15], v[52:55], v[84:87]
	v_mfma_f32_16x16x32_bf16 v[88:91], v[4:7], v[60:63], v[88:91]
	v_mfma_f32_16x16x32_bf16 v[100:103], v[12:15], v[60:63], v[92:95]
	s_setprio 0
	s_setprio 1
	v_mfma_f32_16x16x32_bf16 v[92:95], v[16:19], v[32:35], 0
	v_mfma_f32_16x16x32_bf16 v[32:35], v[24:27], v[32:35], 0
	v_mfma_f32_16x16x32_bf16 v[104:107], v[20:23], v[36:39], v[92:95]
	v_mfma_f32_16x16x32_bf16 v[32:35], v[28:31], v[36:39], v[32:35]
	v_mfma_f32_16x16x32_bf16 v[36:39], v[16:19], v[40:43], 0
	v_mfma_f32_16x16x32_bf16 v[40:43], v[24:27], v[40:43], 0
	v_mfma_f32_16x16x32_bf16 v[36:39], v[20:23], v[44:47], v[36:39]
	v_mfma_f32_16x16x32_bf16 v[40:43], v[28:31], v[44:47], v[40:43]
	v_mfma_f32_16x16x32_bf16 v[44:47], v[16:19], v[48:51], 0
	v_mfma_f32_16x16x32_bf16 v[48:51], v[24:27], v[48:51], 0
	v_mfma_f32_16x16x32_bf16 v[44:47], v[20:23], v[52:55], v[44:47]
	v_mfma_f32_16x16x32_bf16 v[48:51], v[28:31], v[52:55], v[48:51]
	v_mfma_f32_16x16x32_bf16 v[52:55], v[16:19], v[56:59], 0
	v_mfma_f32_16x16x32_bf16 v[56:59], v[24:27], v[56:59], 0
	v_mfma_f32_16x16x32_bf16 v[52:55], v[20:23], v[60:63], v[52:55]
	v_mfma_f32_16x16x32_bf16 v[56:59], v[28:31], v[60:63], v[56:59]
	s_setprio 0
	s_barrier
	s_mov_b32 m0, s68
	v_lshl_add_u64 v[244:245], s[78:79], 0, v[128:129]
	global_load_lds_dwordx4 v[244:245], off
	v_lshl_add_u64 v[136:137], v[244:245], 0, s[0:1]
	s_mov_b32 m0, s69
	v_lshl_add_u64 v[246:247], s[44:45], 0, v[130:131]
	global_load_lds_dwordx4 v[136:137], off
	v_lshl_add_u64 v[136:137], v[244:245], 0, s[2:3]
	s_mov_b32 m0, s70
	s_nop 0
	global_load_lds_dwordx4 v[136:137], off
	v_lshl_add_u64 v[136:137], v[244:245], 0, s[8:9]
	s_mov_b32 m0, s71
	s_nop 0
	global_load_lds_dwordx4 v[136:137], off
	s_mov_b32 m0, s39
	v_lshl_add_u64 v[136:137], v[246:247], 0, s[0:1]
	global_load_lds_dwordx4 v[246:247], off
	s_mov_b32 m0, s56
	s_nop 0
	global_load_lds_dwordx4 v[136:137], off
	ds_read_b128 v[60:63], v143 offset:16384
	ds_read_b128 v[92:95], v143 offset:17408
	ds_read_b128 v[96:99], v143 offset:18432
	ds_read_b128 v[108:111], v143 offset:19456
	ds_read_b128 v[112:115], v143 offset:20480
	ds_read_b128 v[116:119], v143 offset:21504
	ds_read_b128 v[120:123], v143 offset:22528
	ds_read_b128 v[124:127], v143 offset:23552
	s_waitcnt vmcnt(16)
	s_waitcnt lgkmcnt(0)
	s_barrier
	s_setprio 1
	s_waitcnt lgkmcnt(0)
	v_mfma_f32_16x16x32_bf16 v[146:149], v[0:3], v[60:63], 0
	v_mfma_f32_16x16x32_bf16 v[154:157], v[0:3], v[96:99], 0
	v_mfma_f32_16x16x32_bf16 v[162:165], v[0:3], v[112:115], 0
	v_mfma_f32_16x16x32_bf16 v[0:3], v[0:3], v[120:123], 0
	v_mfma_f32_16x16x32_bf16 v[146:149], v[4:7], v[92:95], v[146:149]
	v_mfma_f32_16x16x32_bf16 v[154:157], v[4:7], v[108:111], v[154:157]
	v_mfma_f32_16x16x32_bf16 v[162:165], v[4:7], v[116:119], v[162:165]
	v_mfma_f32_16x16x32_bf16 v[0:3], v[4:7], v[124:127], v[0:3]
	v_mfma_f32_16x16x32_bf16 v[4:7], v[8:11], v[120:123], 0
	v_mfma_f32_16x16x32_bf16 v[150:153], v[8:11], v[60:63], 0
	v_mfma_f32_16x16x32_bf16 v[158:161], v[8:11], v[96:99], 0
	v_mfma_f32_16x16x32_bf16 v[166:169], v[8:11], v[112:115], 0
	v_mfma_f32_16x16x32_bf16 v[4:7], v[12:15], v[124:127], v[4:7]
	v_mfma_f32_16x16x32_bf16 v[150:153], v[12:15], v[92:95], v[150:153]
	v_mfma_f32_16x16x32_bf16 v[158:161], v[12:15], v[108:111], v[158:161]
	v_mfma_f32_16x16x32_bf16 v[166:169], v[12:15], v[116:119], v[166:169]
	s_setprio 0
	s_setprio 1
	v_mfma_f32_16x16x32_bf16 v[12:15], v[24:27], v[60:63], 0
	v_mfma_f32_16x16x32_bf16 v[170:173], v[28:31], v[92:95], v[12:15]
	v_mfma_f32_16x16x32_bf16 v[12:15], v[16:19], v[96:99], 0
	v_mfma_f32_16x16x32_bf16 v[174:177], v[20:23], v[108:111], v[12:15]
	v_mfma_f32_16x16x32_bf16 v[12:15], v[24:27], v[96:99], 0
	v_mfma_f32_16x16x32_bf16 v[178:181], v[28:31], v[108:111], v[12:15]
	v_mfma_f32_16x16x32_bf16 v[12:15], v[16:19], v[112:115], 0
	v_mfma_f32_16x16x32_bf16 v[182:185], v[20:23], v[116:119], v[12:15]
	v_mfma_f32_16x16x32_bf16 v[12:15], v[24:27], v[112:115], 0
	v_mfma_f32_16x16x32_bf16 v[8:11], v[16:19], v[60:63], 0
	v_mfma_f32_16x16x32_bf16 v[186:189], v[28:31], v[116:119], v[12:15]
	v_mfma_f32_16x16x32_bf16 v[12:15], v[16:19], v[120:123], 0
	v_mfma_f32_16x16x32_bf16 v[8:11], v[20:23], v[92:95], v[8:11]
	v_mfma_f32_16x16x32_bf16 v[190:193], v[20:23], v[124:127], v[12:15]
	v_mfma_f32_16x16x32_bf16 v[12:15], v[24:27], v[120:123], 0
	v_mfma_f32_16x16x32_bf16 v[194:197], v[28:31], v[124:127], v[12:15]
	s_setprio 0
	s_barrier
	s_add_i32 s79, 0, 0x1c000
	v_add_u32_e32 v136, s79, v140
	s_nop 2
	s_mov_b32 m0, s57
	v_lshl_add_u64 v[92:93], v[246:247], 0, s[2:3]
	global_load_lds_dwordx4 v[92:93], off
	v_lshl_add_u64 v[92:93], v[246:247], 0, s[8:9]
	s_mov_b32 m0, s58
	s_nop 0
	global_load_lds_dwordx4 v[92:93], off
	ds_read_b128 v[12:15], v144
	ds_read_b128 v[20:23], v144 offset:1024
	ds_read_b128 v[24:27], v144 offset:2048
	ds_read_b128 v[198:201], v144 offset:3072
	ds_read_b128 v[202:205], v136
	ds_read_b128 v[206:209], v136 offset:1024
	ds_read_b128 v[212:215], v136 offset:2048
	ds_read_b128 v[216:219], v136 offset:3072
	ds_read_b128 v[16:19], v143 offset:32768
	ds_read_b128 v[28:31], v143 offset:33792
	ds_read_b128 v[60:63], v143 offset:34816
	ds_read_b128 v[220:223], v143 offset:35840
	ds_read_b128 v[224:227], v143 offset:36864
	ds_read_b128 v[228:231], v143 offset:37888
	ds_read_b128 v[232:235], v143 offset:38912
	ds_read_b128 v[236:239], v143 offset:39936
	s_waitcnt vmcnt(8)
	s_waitcnt lgkmcnt(0)
	s_barrier
	s_setprio 1
	s_waitcnt lgkmcnt(0)
	v_mfma_f32_16x16x32_bf16 v[64:67], v[12:15], v[16:19], v[64:67]
	v_mfma_f32_16x16x32_bf16 v[124:127], v[20:23], v[28:31], v[64:67]
	v_mfma_f32_16x16x32_bf16 v[64:67], v[24:27], v[16:19], v[68:71]
	v_mfma_f32_16x16x32_bf16 v[112:115], v[198:201], v[28:31], v[64:67]
	v_mfma_f32_16x16x32_bf16 v[64:67], v[12:15], v[60:63], v[72:75]
	v_mfma_f32_16x16x32_bf16 v[108:111], v[20:23], v[220:223], v[64:67]
	v_mfma_f32_16x16x32_bf16 v[64:67], v[24:27], v[60:63], v[76:79]
	v_mfma_f32_16x16x32_bf16 v[96:99], v[198:201], v[220:223], v[64:67]
	v_mfma_f32_16x16x32_bf16 v[64:67], v[12:15], v[224:227], v[80:83]
	v_mfma_f32_16x16x32_bf16 v[92:95], v[20:23], v[228:231], v[64:67]
	v_mfma_f32_16x16x32_bf16 v[64:67], v[24:27], v[224:227], v[84:87]
	v_mfma_f32_16x16x32_bf16 v[80:83], v[198:201], v[228:231], v[64:67]
	v_mfma_f32_16x16x32_bf16 v[64:67], v[12:15], v[232:235], v[88:91]
	v_mfma_f32_16x16x32_bf16 v[76:79], v[20:23], v[236:239], v[64:67]
	v_mfma_f32_16x16x32_bf16 v[64:67], v[24:27], v[232:235], v[100:103]
	v_mfma_f32_16x16x32_bf16 v[64:67], v[198:201], v[236:239], v[64:67]
	s_setprio 0
	s_setprio 1
	v_mfma_f32_16x16x32_bf16 v[68:71], v[202:205], v[16:19], v[104:107]
	v_mfma_f32_16x16x32_bf16 v[16:19], v[212:215], v[16:19], v[32:35]
	v_mfma_f32_16x16x32_bf16 v[116:119], v[216:219], v[28:31], v[16:19]
	v_mfma_f32_16x16x32_bf16 v[16:19], v[202:205], v[60:63], v[36:39]
	v_mfma_f32_16x16x32_bf16 v[104:107], v[206:209], v[220:223], v[16:19]
	v_mfma_f32_16x16x32_bf16 v[16:19], v[212:215], v[60:63], v[40:43]
	v_mfma_f32_16x16x32_bf16 v[100:103], v[216:219], v[220:223], v[16:19]
	v_mfma_f32_16x16x32_bf16 v[16:19], v[202:205], v[224:227], v[44:47]
	v_mfma_f32_16x16x32_bf16 v[88:91], v[206:209], v[228:231], v[16:19]
	v_mfma_f32_16x16x32_bf16 v[16:19], v[212:215], v[224:227], v[48:51]
	v_mfma_f32_16x16x32_bf16 v[84:87], v[216:219], v[228:231], v[16:19]
	v_mfma_f32_16x16x32_bf16 v[16:19], v[202:205], v[232:235], v[52:55]
	v_mfma_f32_16x16x32_bf16 v[72:75], v[206:209], v[236:239], v[16:19]
	v_mfma_f32_16x16x32_bf16 v[16:19], v[212:215], v[232:235], v[56:59]
	v_mfma_f32_16x16x32_bf16 v[120:123], v[206:209], v[28:31], v[68:71]
	v_mfma_f32_16x16x32_bf16 v[68:71], v[216:219], v[236:239], v[16:19]
	s_setprio 0
	s_barrier
	s_add_i32 s77, s72, s53
	s_nop 2
	v_lshl_add_u64 v[16:17], v[244:245], 0, s[18:19]
	s_mov_b32 m0, s77
	s_add_i32 s78, s77, 0x2000
	global_load_lds_dwordx4 v[16:17], off
	v_lshl_add_u64 v[16:17], v[244:245], 0, s[20:21]
	s_mov_b32 m0, s78
	s_add_i32 s79, s79, s53
	global_load_lds_dwordx4 v[16:17], off
	v_lshl_add_u64 v[16:17], v[244:245], 0, s[22:23]
	s_mov_b32 m0, s79
	s_add_i32 s80, s79, 0x2000
	global_load_lds_dwordx4 v[16:17], off
	v_lshl_add_u64 v[16:17], v[244:245], 0, s[24:25]
	s_mov_b32 m0, s80
	s_nop 0
	global_load_lds_dwordx4 v[16:17], off
	v_lshl_add_u64 v[16:17], v[246:247], 0, s[18:19]
	s_mov_b32 m0, s60
	s_nop 0
	global_load_lds_dwordx4 v[16:17], off
	v_lshl_add_u64 v[16:17], v[246:247], 0, s[20:21]
	s_mov_b32 m0, s61
	s_nop 0
	global_load_lds_dwordx4 v[16:17], off
	ds_read_b128 v[36:39], v143 offset:49152
	ds_read_b128 v[40:43], v143 offset:50176
	ds_read_b128 v[220:223], v143 offset:51200
	ds_read_b128 v[224:227], v143 offset:52224
	ds_read_b128 v[228:231], v143 offset:53248
	ds_read_b128 v[232:235], v143 offset:54272
	ds_read_b128 v[236:239], v143 offset:55296
	ds_read_b128 v[240:243], v143 offset:56320
	s_waitcnt vmcnt(8)
	s_waitcnt lgkmcnt(0)
	s_barrier
	s_setprio 1
	s_waitcnt lgkmcnt(0)
	v_mfma_f32_16x16x32_bf16 v[16:19], v[12:15], v[36:39], v[146:149]
	v_mfma_f32_16x16x32_bf16 v[60:63], v[20:23], v[40:43], v[16:19]
	v_mfma_f32_16x16x32_bf16 v[16:19], v[24:27], v[36:39], v[150:153]
	v_mfma_f32_16x16x32_bf16 v[48:51], v[198:201], v[40:43], v[16:19]
	v_mfma_f32_16x16x32_bf16 v[16:19], v[12:15], v[220:223], v[154:157]
	v_mfma_f32_16x16x32_bf16 v[44:47], v[20:23], v[224:227], v[16:19]
	v_mfma_f32_16x16x32_bf16 v[16:19], v[24:27], v[220:223], v[158:161]
	v_mfma_f32_16x16x32_bf16 v[32:35], v[198:201], v[224:227], v[16:19]
	v_mfma_f32_16x16x32_bf16 v[16:19], v[12:15], v[228:231], v[162:165]
	v_mfma_f32_16x16x32_bf16 v[0:3], v[12:15], v[236:239], v[0:3]
	v_mfma_f32_16x16x32_bf16 v[28:31], v[20:23], v[232:235], v[16:19]
	v_mfma_f32_16x16x32_bf16 v[16:19], v[24:27], v[228:231], v[166:169]
	v_mfma_f32_16x16x32_bf16 v[12:15], v[20:23], v[240:243], v[0:3]
	v_mfma_f32_16x16x32_bf16 v[0:3], v[24:27], v[236:239], v[4:7]
	v_mfma_f32_16x16x32_bf16 v[16:19], v[198:201], v[232:235], v[16:19]
	v_mfma_f32_16x16x32_bf16 v[0:3], v[198:201], v[240:243], v[0:3]
	s_setprio 0
	s_setprio 1
	v_mfma_f32_16x16x32_bf16 v[4:7], v[202:205], v[36:39], v[8:11]
	v_mfma_f32_16x16x32_bf16 v[56:59], v[206:209], v[40:43], v[4:7]
	v_mfma_f32_16x16x32_bf16 v[4:7], v[212:215], v[36:39], v[170:173]
	v_mfma_f32_16x16x32_bf16 v[52:55], v[216:219], v[40:43], v[4:7]
	v_mfma_f32_16x16x32_bf16 v[4:7], v[202:205], v[220:223], v[174:177]
	v_mfma_f32_16x16x32_bf16 v[40:43], v[206:209], v[224:227], v[4:7]
	v_mfma_f32_16x16x32_bf16 v[4:7], v[212:215], v[220:223], v[178:181]
	v_mfma_f32_16x16x32_bf16 v[36:39], v[216:219], v[224:227], v[4:7]
	v_mfma_f32_16x16x32_bf16 v[4:7], v[202:205], v[228:231], v[182:185]
	v_mfma_f32_16x16x32_bf16 v[24:27], v[206:209], v[232:235], v[4:7]
	v_mfma_f32_16x16x32_bf16 v[4:7], v[212:215], v[228:231], v[186:189]
	v_mfma_f32_16x16x32_bf16 v[20:23], v[216:219], v[232:235], v[4:7]
	v_mfma_f32_16x16x32_bf16 v[4:7], v[202:205], v[236:239], v[190:193]
	v_mfma_f32_16x16x32_bf16 v[8:11], v[206:209], v[240:243], v[4:7]
	v_mfma_f32_16x16x32_bf16 v[4:7], v[212:215], v[236:239], v[194:197]
	v_mfma_f32_16x16x32_bf16 v[4:7], v[216:219], v[240:243], v[4:7]
	s_setprio 0
	s_barrier
.LBB0_175:
	s_add_i32 s29, s29, 2
	s_mov_b32 s44, s29
	s_ashr_i32 s45, s44, 31
	s_lshl_b64 s[82:83], s[44:45], 7
	s_add_u32 s45, s82, 0x100
	s_addc_u32 s81, s83, 0
	s_add_u32 s84, s42, s45
	s_addc_u32 s85, s43, s81
	s_add_u32 s86, s40, s45
	s_addc_u32 s81, s41, s81
	s_cmp_eq_u32 s44, 14
	s_cselect_b32 s45, s75, s85
	s_cselect_b32 s44, s76, s84
	s_cselect_b32 s85, s31, s81
	s_cselect_b32 s84, s74, s86
	s_add_u32 s82, s42, s82
	s_addc_u32 s83, s43, s83
	v_lshl_add_u64 v[212:213], s[82:83], 0, v[130:131]
	s_mov_b32 m0, s66
	v_lshl_add_u64 v[214:215], v[212:213], 0, s[22:23]
	global_load_lds_dwordx4 v[214:215], off
	v_lshl_add_u64 v[212:213], v[212:213], 0, s[24:25]
	s_mov_b32 m0, s67
	s_nop 0
	global_load_lds_dwordx4 v[212:213], off
	ds_read_b128 v[146:149], v141
	ds_read_b128 v[150:153], v141 offset:1024
	ds_read_b128 v[154:157], v141 offset:2048
	ds_read_b128 v[158:161], v141 offset:3072
	ds_read_b128 v[162:165], v142
	ds_read_b128 v[166:169], v142 offset:1024
	ds_read_b128 v[170:173], v142 offset:2048
	ds_read_b128 v[174:177], v142 offset:3072
	ds_read_b128 v[178:181], v143
	ds_read_b128 v[182:185], v143 offset:1024
	ds_read_b128 v[186:189], v143 offset:2048
	ds_read_b128 v[190:193], v143 offset:3072
	ds_read_b128 v[194:197], v143 offset:4096
	ds_read_b128 v[198:201], v143 offset:5120
	ds_read_b128 v[202:205], v143 offset:6144
	ds_read_b128 v[206:209], v143 offset:7168
	s_waitcnt vmcnt(8)
	s_waitcnt lgkmcnt(0)
	s_barrier
	s_setprio 1
	s_waitcnt lgkmcnt(0)
	v_mfma_f32_16x16x32_bf16 v[124:127], v[146:149], v[178:181], v[124:127]
	v_mfma_f32_16x16x32_bf16 v[112:115], v[154:157], v[178:181], v[112:115]
	v_mfma_f32_16x16x32_bf16 v[108:111], v[146:149], v[186:189], v[108:111]
	v_mfma_f32_16x16x32_bf16 v[96:99], v[154:157], v[186:189], v[96:99]
	v_mfma_f32_16x16x32_bf16 v[92:95], v[146:149], v[194:197], v[92:95]
	v_mfma_f32_16x16x32_bf16 v[80:83], v[154:157], v[194:197], v[80:83]
	v_mfma_f32_16x16x32_bf16 v[76:79], v[146:149], v[202:205], v[76:79]
	v_mfma_f32_16x16x32_bf16 v[64:67], v[154:157], v[202:205], v[64:67]
	v_mfma_f32_16x16x32_bf16 v[124:127], v[150:153], v[182:185], v[124:127]
	v_mfma_f32_16x16x32_bf16 v[112:115], v[158:161], v[182:185], v[112:115]
	v_mfma_f32_16x16x32_bf16 v[108:111], v[150:153], v[190:193], v[108:111]
	v_mfma_f32_16x16x32_bf16 v[96:99], v[158:161], v[190:193], v[96:99]
	v_mfma_f32_16x16x32_bf16 v[92:95], v[150:153], v[198:201], v[92:95]
	v_mfma_f32_16x16x32_bf16 v[80:83], v[158:161], v[198:201], v[80:83]
	v_mfma_f32_16x16x32_bf16 v[76:79], v[150:153], v[206:209], v[76:79]
	v_mfma_f32_16x16x32_bf16 v[64:67], v[158:161], v[206:209], v[64:67]
	s_setprio 0
	s_setprio 1
	v_mfma_f32_16x16x32_bf16 v[120:123], v[162:165], v[178:181], v[120:123]
	v_mfma_f32_16x16x32_bf16 v[116:119], v[170:173], v[178:181], v[116:119]
	v_mfma_f32_16x16x32_bf16 v[104:107], v[162:165], v[186:189], v[104:107]
	v_mfma_f32_16x16x32_bf16 v[100:103], v[170:173], v[186:189], v[100:103]
	v_mfma_f32_16x16x32_bf16 v[88:91], v[162:165], v[194:197], v[88:91]
	v_mfma_f32_16x16x32_bf16 v[84:87], v[170:173], v[194:197], v[84:87]
	v_mfma_f32_16x16x32_bf16 v[72:75], v[162:165], v[202:205], v[72:75]
	v_mfma_f32_16x16x32_bf16 v[68:71], v[170:173], v[202:205], v[68:71]
	v_mfma_f32_16x16x32_bf16 v[120:123], v[166:169], v[182:185], v[120:123]
	v_mfma_f32_16x16x32_bf16 v[116:119], v[174:177], v[182:185], v[116:119]
	v_mfma_f32_16x16x32_bf16 v[104:107], v[166:169], v[190:193], v[104:107]
	v_mfma_f32_16x16x32_bf16 v[100:103], v[174:177], v[190:193], v[100:103]
	v_mfma_f32_16x16x32_bf16 v[88:91], v[166:169], v[198:201], v[88:91]
	v_mfma_f32_16x16x32_bf16 v[84:87], v[174:177], v[198:201], v[84:87]
	v_mfma_f32_16x16x32_bf16 v[72:75], v[166:169], v[206:209], v[72:75]
	v_mfma_f32_16x16x32_bf16 v[68:71], v[174:177], v[206:209], v[68:71]
	s_setprio 0
	s_barrier
	s_mov_b32 m0, s68
	v_lshl_add_u64 v[212:213], s[84:85], 0, v[128:129]
	global_load_lds_dwordx4 v[212:213], off
	v_lshl_add_u64 v[214:215], v[212:213], 0, s[0:1]
	s_mov_b32 m0, s69
	s_nop 0
	global_load_lds_dwordx4 v[214:215], off
	v_lshl_add_u64 v[214:215], v[212:213], 0, s[2:3]
	s_mov_b32 m0, s70
	s_nop 0
	global_load_lds_dwordx4 v[214:215], off
	v_lshl_add_u64 v[214:215], v[212:213], 0, s[8:9]
	s_mov_b32 m0, s71
	s_nop 0
	global_load_lds_dwordx4 v[214:215], off
	v_lshl_add_u64 v[214:215], s[44:45], 0, v[130:131]
	s_mov_b32 m0, s39
	v_lshl_add_u64 v[216:217], v[214:215], 0, s[0:1]
	global_load_lds_dwordx4 v[214:215], off
	s_mov_b32 m0, s56
	s_nop 0
	global_load_lds_dwordx4 v[216:217], off
	ds_read_b128 v[178:181], v143 offset:16384
	ds_read_b128 v[182:185], v143 offset:17408
	ds_read_b128 v[186:189], v143 offset:18432
	ds_read_b128 v[190:193], v143 offset:19456
	ds_read_b128 v[194:197], v143 offset:20480
	ds_read_b128 v[198:201], v143 offset:21504
	ds_read_b128 v[202:205], v143 offset:22528
	ds_read_b128 v[206:209], v143 offset:23552
	s_waitcnt vmcnt(8)
	s_waitcnt lgkmcnt(0)
	s_barrier
	s_setprio 1
	s_waitcnt lgkmcnt(0)
	v_mfma_f32_16x16x32_bf16 v[60:63], v[146:149], v[178:181], v[60:63]
	v_mfma_f32_16x16x32_bf16 v[48:51], v[154:157], v[178:181], v[48:51]
	v_mfma_f32_16x16x32_bf16 v[44:47], v[146:149], v[186:189], v[44:47]
	v_mfma_f32_16x16x32_bf16 v[32:35], v[154:157], v[186:189], v[32:35]
	v_mfma_f32_16x16x32_bf16 v[28:31], v[146:149], v[194:197], v[28:31]
	v_mfma_f32_16x16x32_bf16 v[16:19], v[154:157], v[194:197], v[16:19]
	v_mfma_f32_16x16x32_bf16 v[12:15], v[146:149], v[202:205], v[12:15]
	v_mfma_f32_16x16x32_bf16 v[0:3], v[154:157], v[202:205], v[0:3]
	v_mfma_f32_16x16x32_bf16 v[60:63], v[150:153], v[182:185], v[60:63]
	v_mfma_f32_16x16x32_bf16 v[48:51], v[158:161], v[182:185], v[48:51]
	v_mfma_f32_16x16x32_bf16 v[44:47], v[150:153], v[190:193], v[44:47]
	v_mfma_f32_16x16x32_bf16 v[32:35], v[158:161], v[190:193], v[32:35]
	v_mfma_f32_16x16x32_bf16 v[28:31], v[150:153], v[198:201], v[28:31]
	v_mfma_f32_16x16x32_bf16 v[16:19], v[158:161], v[198:201], v[16:19]
	v_mfma_f32_16x16x32_bf16 v[12:15], v[150:153], v[206:209], v[12:15]
	v_mfma_f32_16x16x32_bf16 v[0:3], v[158:161], v[206:209], v[0:3]
	s_setprio 0
	s_setprio 1
	v_mfma_f32_16x16x32_bf16 v[56:59], v[162:165], v[178:181], v[56:59]
	v_mfma_f32_16x16x32_bf16 v[52:55], v[170:173], v[178:181], v[52:55]
	v_mfma_f32_16x16x32_bf16 v[40:43], v[162:165], v[186:189], v[40:43]
	v_mfma_f32_16x16x32_bf16 v[36:39], v[170:173], v[186:189], v[36:39]
	v_mfma_f32_16x16x32_bf16 v[24:27], v[162:165], v[194:197], v[24:27]
	v_mfma_f32_16x16x32_bf16 v[20:23], v[170:173], v[194:197], v[20:23]
	v_mfma_f32_16x16x32_bf16 v[8:11], v[162:165], v[202:205], v[8:11]
	v_mfma_f32_16x16x32_bf16 v[4:7], v[170:173], v[202:205], v[4:7]
	v_mfma_f32_16x16x32_bf16 v[56:59], v[166:169], v[182:185], v[56:59]
	v_mfma_f32_16x16x32_bf16 v[52:55], v[174:177], v[182:185], v[52:55]
	v_mfma_f32_16x16x32_bf16 v[40:43], v[166:169], v[190:193], v[40:43]
	v_mfma_f32_16x16x32_bf16 v[36:39], v[174:177], v[190:193], v[36:39]
	v_mfma_f32_16x16x32_bf16 v[24:27], v[166:169], v[198:201], v[24:27]
	v_mfma_f32_16x16x32_bf16 v[20:23], v[174:177], v[198:201], v[20:23]
	v_mfma_f32_16x16x32_bf16 v[8:11], v[166:169], v[206:209], v[8:11]
	v_mfma_f32_16x16x32_bf16 v[4:7], v[174:177], v[206:209], v[4:7]
	s_setprio 0
	s_barrier
	s_mov_b32 m0, s57
	v_lshl_add_u64 v[216:217], v[214:215], 0, s[2:3]
	global_load_lds_dwordx4 v[216:217], off
	v_lshl_add_u64 v[216:217], v[214:215], 0, s[8:9]
	s_mov_b32 m0, s58
	s_nop 0
	global_load_lds_dwordx4 v[216:217], off
	ds_read_b128 v[146:149], v144
	ds_read_b128 v[150:153], v144 offset:1024
	ds_read_b128 v[154:157], v144 offset:2048
	ds_read_b128 v[158:161], v144 offset:3072
	ds_read_b128 v[162:165], v136
	ds_read_b128 v[166:169], v136 offset:1024
	ds_read_b128 v[170:173], v136 offset:2048
	ds_read_b128 v[174:177], v136 offset:3072
	ds_read_b128 v[178:181], v143 offset:32768
	ds_read_b128 v[182:185], v143 offset:33792
	ds_read_b128 v[186:189], v143 offset:34816
	ds_read_b128 v[190:193], v143 offset:35840
	ds_read_b128 v[194:197], v143 offset:36864
	ds_read_b128 v[198:201], v143 offset:37888
	ds_read_b128 v[202:205], v143 offset:38912
	ds_read_b128 v[206:209], v143 offset:39936
	s_waitcnt vmcnt(8)
	s_waitcnt lgkmcnt(0)
	s_barrier
	s_setprio 1
	s_waitcnt lgkmcnt(0)
	v_mfma_f32_16x16x32_bf16 v[124:127], v[146:149], v[178:181], v[124:127]
	v_mfma_f32_16x16x32_bf16 v[112:115], v[154:157], v[178:181], v[112:115]
	v_mfma_f32_16x16x32_bf16 v[108:111], v[146:149], v[186:189], v[108:111]
	v_mfma_f32_16x16x32_bf16 v[96:99], v[154:157], v[186:189], v[96:99]
	v_mfma_f32_16x16x32_bf16 v[92:95], v[146:149], v[194:197], v[92:95]
	v_mfma_f32_16x16x32_bf16 v[80:83], v[154:157], v[194:197], v[80:83]
	v_mfma_f32_16x16x32_bf16 v[76:79], v[146:149], v[202:205], v[76:79]
	v_mfma_f32_16x16x32_bf16 v[64:67], v[154:157], v[202:205], v[64:67]
	v_mfma_f32_16x16x32_bf16 v[124:127], v[150:153], v[182:185], v[124:127]
	v_mfma_f32_16x16x32_bf16 v[112:115], v[158:161], v[182:185], v[112:115]
	v_mfma_f32_16x16x32_bf16 v[108:111], v[150:153], v[190:193], v[108:111]
	v_mfma_f32_16x16x32_bf16 v[96:99], v[158:161], v[190:193], v[96:99]
	v_mfma_f32_16x16x32_bf16 v[92:95], v[150:153], v[198:201], v[92:95]
	v_mfma_f32_16x16x32_bf16 v[80:83], v[158:161], v[198:201], v[80:83]
	v_mfma_f32_16x16x32_bf16 v[76:79], v[150:153], v[206:209], v[76:79]
	v_mfma_f32_16x16x32_bf16 v[64:67], v[158:161], v[206:209], v[64:67]
	s_setprio 0
	s_setprio 1
	v_mfma_f32_16x16x32_bf16 v[120:123], v[162:165], v[178:181], v[120:123]
	v_mfma_f32_16x16x32_bf16 v[116:119], v[170:173], v[178:181], v[116:119]
	v_mfma_f32_16x16x32_bf16 v[104:107], v[162:165], v[186:189], v[104:107]
	v_mfma_f32_16x16x32_bf16 v[100:103], v[170:173], v[186:189], v[100:103]
	v_mfma_f32_16x16x32_bf16 v[88:91], v[162:165], v[194:197], v[88:91]
	v_mfma_f32_16x16x32_bf16 v[84:87], v[170:173], v[194:197], v[84:87]
	v_mfma_f32_16x16x32_bf16 v[72:75], v[162:165], v[202:205], v[72:75]
	v_mfma_f32_16x16x32_bf16 v[68:71], v[170:173], v[202:205], v[68:71]
	v_mfma_f32_16x16x32_bf16 v[120:123], v[166:169], v[182:185], v[120:123]
	v_mfma_f32_16x16x32_bf16 v[116:119], v[174:177], v[182:185], v[116:119]
	v_mfma_f32_16x16x32_bf16 v[104:107], v[166:169], v[190:193], v[104:107]
	v_mfma_f32_16x16x32_bf16 v[100:103], v[174:177], v[190:193], v[100:103]
	v_mfma_f32_16x16x32_bf16 v[88:91], v[166:169], v[198:201], v[88:91]
	v_mfma_f32_16x16x32_bf16 v[84:87], v[174:177], v[198:201], v[84:87]
	v_mfma_f32_16x16x32_bf16 v[72:75], v[166:169], v[206:209], v[72:75]
	v_mfma_f32_16x16x32_bf16 v[68:71], v[174:177], v[206:209], v[68:71]
	s_setprio 0
	s_barrier
	s_mov_b32 m0, s77
	v_lshl_add_u64 v[216:217], v[212:213], 0, s[18:19]
	global_load_lds_dwordx4 v[216:217], off
	v_lshl_add_u64 v[216:217], v[212:213], 0, s[20:21]
	s_mov_b32 m0, s78
	s_nop 0
	global_load_lds_dwordx4 v[216:217], off
	v_lshl_add_u64 v[216:217], v[212:213], 0, s[22:23]
	s_mov_b32 m0, s79
	v_lshl_add_u64 v[212:213], v[212:213], 0, s[24:25]
	global_load_lds_dwordx4 v[216:217], off
	s_mov_b32 m0, s80
	s_nop 0
	global_load_lds_dwordx4 v[212:213], off
	v_lshl_add_u64 v[212:213], v[214:215], 0, s[18:19]
	s_mov_b32 m0, s60
	s_nop 0
	global_load_lds_dwordx4 v[212:213], off
	v_lshl_add_u64 v[212:213], v[214:215], 0, s[20:21]
	s_mov_b32 m0, s61
	s_nop 0
	global_load_lds_dwordx4 v[212:213], off
	ds_read_b128 v[178:181], v143 offset:49152
	ds_read_b128 v[182:185], v143 offset:50176
	ds_read_b128 v[186:189], v143 offset:51200
	ds_read_b128 v[190:193], v143 offset:52224
	ds_read_b128 v[194:197], v143 offset:53248
	ds_read_b128 v[198:201], v143 offset:54272
	ds_read_b128 v[202:205], v143 offset:55296
	ds_read_b128 v[206:209], v143 offset:56320
	s_waitcnt vmcnt(8)
	s_waitcnt lgkmcnt(0)
	s_barrier
	s_setprio 1
	s_waitcnt lgkmcnt(0)
	v_mfma_f32_16x16x32_bf16 v[60:63], v[146:149], v[178:181], v[60:63]
	v_mfma_f32_16x16x32_bf16 v[48:51], v[154:157], v[178:181], v[48:51]
	v_mfma_f32_16x16x32_bf16 v[44:47], v[146:149], v[186:189], v[44:47]
	v_mfma_f32_16x16x32_bf16 v[32:35], v[154:157], v[186:189], v[32:35]
	v_mfma_f32_16x16x32_bf16 v[28:31], v[146:149], v[194:197], v[28:31]
	v_mfma_f32_16x16x32_bf16 v[16:19], v[154:157], v[194:197], v[16:19]
	v_mfma_f32_16x16x32_bf16 v[12:15], v[146:149], v[202:205], v[12:15]
	v_mfma_f32_16x16x32_bf16 v[0:3], v[154:157], v[202:205], v[0:3]
	v_mfma_f32_16x16x32_bf16 v[60:63], v[150:153], v[182:185], v[60:63]
	v_mfma_f32_16x16x32_bf16 v[48:51], v[158:161], v[182:185], v[48:51]
	v_mfma_f32_16x16x32_bf16 v[44:47], v[150:153], v[190:193], v[44:47]
	v_mfma_f32_16x16x32_bf16 v[32:35], v[158:161], v[190:193], v[32:35]
	v_mfma_f32_16x16x32_bf16 v[28:31], v[150:153], v[198:201], v[28:31]
	v_mfma_f32_16x16x32_bf16 v[16:19], v[158:161], v[198:201], v[16:19]
	v_mfma_f32_16x16x32_bf16 v[12:15], v[150:153], v[206:209], v[12:15]
	v_mfma_f32_16x16x32_bf16 v[0:3], v[158:161], v[206:209], v[0:3]
	s_setprio 0
	s_setprio 1
	v_mfma_f32_16x16x32_bf16 v[56:59], v[162:165], v[178:181], v[56:59]
	v_mfma_f32_16x16x32_bf16 v[52:55], v[170:173], v[178:181], v[52:55]
	v_mfma_f32_16x16x32_bf16 v[40:43], v[162:165], v[186:189], v[40:43]
	v_mfma_f32_16x16x32_bf16 v[36:39], v[170:173], v[186:189], v[36:39]
	v_mfma_f32_16x16x32_bf16 v[24:27], v[162:165], v[194:197], v[24:27]
	v_mfma_f32_16x16x32_bf16 v[20:23], v[170:173], v[194:197], v[20:23]
	v_mfma_f32_16x16x32_bf16 v[8:11], v[162:165], v[202:205], v[8:11]
	v_mfma_f32_16x16x32_bf16 v[4:7], v[170:173], v[202:205], v[4:7]
	v_mfma_f32_16x16x32_bf16 v[56:59], v[166:169], v[182:185], v[56:59]
	v_mfma_f32_16x16x32_bf16 v[52:55], v[174:177], v[182:185], v[52:55]
	v_mfma_f32_16x16x32_bf16 v[40:43], v[166:169], v[190:193], v[40:43]
	v_mfma_f32_16x16x32_bf16 v[36:39], v[174:177], v[190:193], v[36:39]
	v_mfma_f32_16x16x32_bf16 v[24:27], v[166:169], v[198:201], v[24:27]
	v_mfma_f32_16x16x32_bf16 v[20:23], v[174:177], v[198:201], v[20:23]
	v_mfma_f32_16x16x32_bf16 v[8:11], v[166:169], v[206:209], v[8:11]
	v_mfma_f32_16x16x32_bf16 v[4:7], v[174:177], v[206:209], v[4:7]
	s_setprio 0
	s_barrier
	s_cmp_gt_u32 s29, 13
	s_cbranch_scc0 .LBB0_175
	s_and_b64 vcc, exec, s[26:27]
	s_cbranch_vccz .LBB0_178
	s_barrier

.LBB0_255:
	s_add_i32 s73, s73, 2
	s_mov_b32 s74, s73
	s_ashr_i32 s75, s74, 31
	s_lshl_b64 s[76:77], s[74:75], 7
	s_add_u32 s75, s76, 0x100
	s_addc_u32 s78, s77, 0
	s_add_u32 s79, s40, s75
	s_addc_u32 s80, s41, s78
	s_add_u32 s81, s38, s75
	s_addc_u32 s78, s39, s78
	s_cmp_eq_u32 s74, 42
	s_cselect_b32 s75, s1, s80
	s_cselect_b32 s74, s0, s79
	s_cselect_b32 s79, s43, s78
	s_cselect_b32 s78, s42, s81
	v_lshl_add_u64 v[208:209], v[136:137], 0, s[76:77]
	v_lshl_add_u64 v[212:213], v[208:209], 0, s[20:21]
	s_add_i32 m0, s53, 0xc000
	s_nop 0
	global_load_lds_dwordx4 v[212:213], off
	v_lshl_add_u64 v[208:209], v[208:209], 0, s[22:23]
	s_add_i32 m0, s53, 0xe000
	s_nop 0
	global_load_lds_dwordx4 v[208:209], off
	ds_read_b128 v[144:147], v141
	ds_read_b128 v[148:151], v141 offset:1024
	ds_read_b128 v[152:155], v141 offset:2048
	ds_read_b128 v[156:159], v141 offset:3072
	ds_read_b128 v[160:163], v142
	ds_read_b128 v[164:167], v142 offset:1024
	ds_read_b128 v[168:171], v142 offset:2048
	ds_read_b128 v[172:175], v142 offset:3072
	ds_read_b128 v[176:179], v143
	ds_read_b128 v[180:183], v143 offset:1024
	ds_read_b128 v[184:187], v143 offset:2048
	ds_read_b128 v[188:191], v143 offset:3072
	ds_read_b128 v[192:195], v143 offset:4096
	ds_read_b128 v[196:199], v143 offset:5120
	ds_read_b128 v[200:203], v143 offset:6144
	ds_read_b128 v[204:207], v143 offset:7168
	s_waitcnt vmcnt(8)
	s_waitcnt lgkmcnt(0)
	s_barrier
	s_setprio 1
	s_waitcnt lgkmcnt(0)
	v_mfma_f32_16x16x32_bf16 v[124:127], v[144:147], v[176:179], v[124:127]
	v_mfma_f32_16x16x32_bf16 v[120:123], v[152:155], v[176:179], v[120:123]
	v_mfma_f32_16x16x32_bf16 v[116:119], v[144:147], v[184:187], v[116:119]
	v_mfma_f32_16x16x32_bf16 v[112:115], v[152:155], v[184:187], v[112:115]
	v_mfma_f32_16x16x32_bf16 v[100:103], v[144:147], v[192:195], v[100:103]
	v_mfma_f32_16x16x32_bf16 v[96:99], v[152:155], v[192:195], v[96:99]
	v_mfma_f32_16x16x32_bf16 v[84:87], v[144:147], v[200:203], v[84:87]
	v_mfma_f32_16x16x32_bf16 v[80:83], v[152:155], v[200:203], v[80:83]
	v_mfma_f32_16x16x32_bf16 v[124:127], v[148:151], v[180:183], v[124:127]
	v_mfma_f32_16x16x32_bf16 v[120:123], v[156:159], v[180:183], v[120:123]
	v_mfma_f32_16x16x32_bf16 v[116:119], v[148:151], v[188:191], v[116:119]
	v_mfma_f32_16x16x32_bf16 v[112:115], v[156:159], v[188:191], v[112:115]
	v_mfma_f32_16x16x32_bf16 v[100:103], v[148:151], v[196:199], v[100:103]
	v_mfma_f32_16x16x32_bf16 v[96:99], v[156:159], v[196:199], v[96:99]
	v_mfma_f32_16x16x32_bf16 v[84:87], v[148:151], v[204:207], v[84:87]
	v_mfma_f32_16x16x32_bf16 v[80:83], v[156:159], v[204:207], v[80:83]
	s_setprio 0
	s_setprio 1
	v_mfma_f32_16x16x32_bf16 v[108:111], v[160:163], v[176:179], v[108:111]
	v_mfma_f32_16x16x32_bf16 v[104:107], v[168:171], v[176:179], v[104:107]
	v_mfma_f32_16x16x32_bf16 v[92:95], v[160:163], v[184:187], v[92:95]
	v_mfma_f32_16x16x32_bf16 v[88:91], v[168:171], v[184:187], v[88:91]
	v_mfma_f32_16x16x32_bf16 v[76:79], v[160:163], v[192:195], v[76:79]
	v_mfma_f32_16x16x32_bf16 v[72:75], v[168:171], v[192:195], v[72:75]
	v_mfma_f32_16x16x32_bf16 v[68:71], v[160:163], v[200:203], v[68:71]
	v_mfma_f32_16x16x32_bf16 v[64:67], v[168:171], v[200:203], v[64:67]
	v_mfma_f32_16x16x32_bf16 v[108:111], v[164:167], v[180:183], v[108:111]
	v_mfma_f32_16x16x32_bf16 v[104:107], v[172:175], v[180:183], v[104:107]
	v_mfma_f32_16x16x32_bf16 v[92:95], v[164:167], v[188:191], v[92:95]
	v_mfma_f32_16x16x32_bf16 v[88:91], v[172:175], v[188:191], v[88:91]
	v_mfma_f32_16x16x32_bf16 v[76:79], v[164:167], v[196:199], v[76:79]
	v_mfma_f32_16x16x32_bf16 v[72:75], v[172:175], v[196:199], v[72:75]
	v_mfma_f32_16x16x32_bf16 v[68:71], v[164:167], v[204:207], v[68:71]
	v_mfma_f32_16x16x32_bf16 v[64:67], v[172:175], v[204:207], v[64:67]
	s_setprio 0
	s_barrier
	s_add_i32 s76, s63, s52
	v_lshl_add_u64 v[208:209], s[78:79], 0, v[130:131]
	s_mov_b32 m0, s76
	s_nop 0
	global_load_lds_dwordx4 v[208:209], off
	v_lshl_add_u64 v[212:213], v[208:209], 0, s[2:3]
	s_add_i32 m0, s76, 0x2000
	s_add_i32 s76, s64, s52
	global_load_lds_dwordx4 v[212:213], off
	v_lshl_add_u64 v[212:213], v[208:209], 0, s[8:9]
	s_mov_b32 m0, s76
	s_nop 0
	global_load_lds_dwordx4 v[212:213], off
	v_lshl_add_u64 v[212:213], v[208:209], 0, s[14:15]
	s_add_i32 m0, s76, 0x2000
	s_nop 0
	global_load_lds_dwordx4 v[212:213], off
	v_lshl_add_u64 v[212:213], s[74:75], 0, v[128:129]
	s_mov_b32 m0, s53
	v_lshl_add_u64 v[214:215], v[212:213], 0, s[2:3]
	global_load_lds_dwordx4 v[212:213], off
	s_mov_b32 m0, s54
	s_nop 0
	global_load_lds_dwordx4 v[214:215], off
	ds_read_b128 v[176:179], v143 offset:16384
	ds_read_b128 v[180:183], v143 offset:17408
	ds_read_b128 v[184:187], v143 offset:18432
	ds_read_b128 v[188:191], v143 offset:19456
	ds_read_b128 v[192:195], v143 offset:20480
	ds_read_b128 v[196:199], v143 offset:21504
	ds_read_b128 v[200:203], v143 offset:22528
	ds_read_b128 v[204:207], v143 offset:23552
	s_waitcnt vmcnt(8)
	s_waitcnt lgkmcnt(0)
	s_barrier
	s_setprio 1
	s_waitcnt lgkmcnt(0)
	v_mfma_f32_16x16x32_bf16 v[60:63], v[144:147], v[176:179], v[60:63]
	v_mfma_f32_16x16x32_bf16 v[56:59], v[152:155], v[176:179], v[56:59]
	v_mfma_f32_16x16x32_bf16 v[52:55], v[144:147], v[184:187], v[52:55]
	v_mfma_f32_16x16x32_bf16 v[48:51], v[152:155], v[184:187], v[48:51]
	v_mfma_f32_16x16x32_bf16 v[36:39], v[144:147], v[192:195], v[36:39]
	v_mfma_f32_16x16x32_bf16 v[32:35], v[152:155], v[192:195], v[32:35]
	v_mfma_f32_16x16x32_bf16 v[20:23], v[144:147], v[200:203], v[20:23]
	v_mfma_f32_16x16x32_bf16 v[16:19], v[152:155], v[200:203], v[16:19]
	v_mfma_f32_16x16x32_bf16 v[60:63], v[148:151], v[180:183], v[60:63]
	v_mfma_f32_16x16x32_bf16 v[56:59], v[156:159], v[180:183], v[56:59]
	v_mfma_f32_16x16x32_bf16 v[52:55], v[148:151], v[188:191], v[52:55]
	v_mfma_f32_16x16x32_bf16 v[48:51], v[156:159], v[188:191], v[48:51]
	v_mfma_f32_16x16x32_bf16 v[36:39], v[148:151], v[196:199], v[36:39]
	v_mfma_f32_16x16x32_bf16 v[32:35], v[156:159], v[196:199], v[32:35]
	v_mfma_f32_16x16x32_bf16 v[20:23], v[148:151], v[204:207], v[20:23]
	v_mfma_f32_16x16x32_bf16 v[16:19], v[156:159], v[204:207], v[16:19]
	s_setprio 0
	s_setprio 1
	v_mfma_f32_16x16x32_bf16 v[44:47], v[160:163], v[176:179], v[44:47]
	v_mfma_f32_16x16x32_bf16 v[40:43], v[168:171], v[176:179], v[40:43]
	v_mfma_f32_16x16x32_bf16 v[28:31], v[160:163], v[184:187], v[28:31]
	v_mfma_f32_16x16x32_bf16 v[24:27], v[168:171], v[184:187], v[24:27]
	v_mfma_f32_16x16x32_bf16 v[12:15], v[160:163], v[192:195], v[12:15]
	v_mfma_f32_16x16x32_bf16 v[8:11], v[168:171], v[192:195], v[8:11]
	v_mfma_f32_16x16x32_bf16 v[4:7], v[160:163], v[200:203], v[4:7]
	v_mfma_f32_16x16x32_bf16 v[0:3], v[168:171], v[200:203], v[0:3]
	v_mfma_f32_16x16x32_bf16 v[44:47], v[164:167], v[180:183], v[44:47]
	v_mfma_f32_16x16x32_bf16 v[40:43], v[172:175], v[180:183], v[40:43]
	v_mfma_f32_16x16x32_bf16 v[28:31], v[164:167], v[188:191], v[28:31]
	v_mfma_f32_16x16x32_bf16 v[24:27], v[172:175], v[188:191], v[24:27]
	v_mfma_f32_16x16x32_bf16 v[12:15], v[164:167], v[196:199], v[12:15]
	v_mfma_f32_16x16x32_bf16 v[8:11], v[172:175], v[196:199], v[8:11]
	v_mfma_f32_16x16x32_bf16 v[4:7], v[164:167], v[204:207], v[4:7]
	v_mfma_f32_16x16x32_bf16 v[0:3], v[172:175], v[204:207], v[0:3]
	s_setprio 0
	s_barrier
	s_add_i32 s74, 0, 0x18000
	s_add_i32 s75, 0, 0x1c000
	v_add_u32_e32 v156, s74, v140
	v_add_u32_e32 v172, s75, v140
	s_mov_b32 m0, s55
	v_lshl_add_u64 v[214:215], v[212:213], 0, s[8:9]
	global_load_lds_dwordx4 v[214:215], off
	v_lshl_add_u64 v[214:215], v[212:213], 0, s[14:15]
	s_mov_b32 m0, s56
	s_nop 0
	global_load_lds_dwordx4 v[214:215], off
	ds_read_b128 v[144:147], v156
	ds_read_b128 v[148:151], v156 offset:1024
	ds_read_b128 v[152:155], v156 offset:2048
	ds_read_b128 v[156:159], v156 offset:3072
	ds_read_b128 v[160:163], v172
	ds_read_b128 v[164:167], v172 offset:1024
	ds_read_b128 v[168:171], v172 offset:2048
	ds_read_b128 v[172:175], v172 offset:3072
	ds_read_b128 v[176:179], v143 offset:32768
	ds_read_b128 v[180:183], v143 offset:33792
	ds_read_b128 v[184:187], v143 offset:34816
	ds_read_b128 v[188:191], v143 offset:35840
	ds_read_b128 v[192:195], v143 offset:36864
	ds_read_b128 v[196:199], v143 offset:37888
	ds_read_b128 v[200:203], v143 offset:38912
	ds_read_b128 v[204:207], v143 offset:39936
	s_waitcnt vmcnt(8)
	s_waitcnt lgkmcnt(0)
	s_barrier
	s_setprio 1
	s_waitcnt lgkmcnt(0)
	v_mfma_f32_16x16x32_bf16 v[124:127], v[144:147], v[176:179], v[124:127]
	v_mfma_f32_16x16x32_bf16 v[120:123], v[152:155], v[176:179], v[120:123]
	v_mfma_f32_16x16x32_bf16 v[116:119], v[144:147], v[184:187], v[116:119]
	v_mfma_f32_16x16x32_bf16 v[112:115], v[152:155], v[184:187], v[112:115]
	v_mfma_f32_16x16x32_bf16 v[100:103], v[144:147], v[192:195], v[100:103]
	v_mfma_f32_16x16x32_bf16 v[96:99], v[152:155], v[192:195], v[96:99]
	v_mfma_f32_16x16x32_bf16 v[84:87], v[144:147], v[200:203], v[84:87]
	v_mfma_f32_16x16x32_bf16 v[80:83], v[152:155], v[200:203], v[80:83]
	v_mfma_f32_16x16x32_bf16 v[124:127], v[148:151], v[180:183], v[124:127]
	v_mfma_f32_16x16x32_bf16 v[120:123], v[156:159], v[180:183], v[120:123]
	v_mfma_f32_16x16x32_bf16 v[116:119], v[148:151], v[188:191], v[116:119]
	v_mfma_f32_16x16x32_bf16 v[112:115], v[156:159], v[188:191], v[112:115]
	v_mfma_f32_16x16x32_bf16 v[100:103], v[148:151], v[196:199], v[100:103]
	v_mfma_f32_16x16x32_bf16 v[96:99], v[156:159], v[196:199], v[96:99]
	v_mfma_f32_16x16x32_bf16 v[84:87], v[148:151], v[204:207], v[84:87]
	v_mfma_f32_16x16x32_bf16 v[80:83], v[156:159], v[204:207], v[80:83]
	s_setprio 0
	s_setprio 1
	v_mfma_f32_16x16x32_bf16 v[108:111], v[160:163], v[176:179], v[108:111]
	v_mfma_f32_16x16x32_bf16 v[104:107], v[168:171], v[176:179], v[104:107]
	v_mfma_f32_16x16x32_bf16 v[92:95], v[160:163], v[184:187], v[92:95]
	v_mfma_f32_16x16x32_bf16 v[88:91], v[168:171], v[184:187], v[88:91]
	v_mfma_f32_16x16x32_bf16 v[76:79], v[160:163], v[192:195], v[76:79]
	v_mfma_f32_16x16x32_bf16 v[72:75], v[168:171], v[192:195], v[72:75]
	v_mfma_f32_16x16x32_bf16 v[68:71], v[160:163], v[200:203], v[68:71]
	v_mfma_f32_16x16x32_bf16 v[64:67], v[168:171], v[200:203], v[64:67]
	v_mfma_f32_16x16x32_bf16 v[108:111], v[164:167], v[180:183], v[108:111]
	v_mfma_f32_16x16x32_bf16 v[104:107], v[172:175], v[180:183], v[104:107]
	v_mfma_f32_16x16x32_bf16 v[92:95], v[164:167], v[188:191], v[92:95]
	v_mfma_f32_16x16x32_bf16 v[88:91], v[172:175], v[188:191], v[88:91]
	v_mfma_f32_16x16x32_bf16 v[76:79], v[164:167], v[196:199], v[76:79]
	v_mfma_f32_16x16x32_bf16 v[72:75], v[172:175], v[196:199], v[72:75]
	v_mfma_f32_16x16x32_bf16 v[68:71], v[164:167], v[204:207], v[68:71]
	v_mfma_f32_16x16x32_bf16 v[64:67], v[172:175], v[204:207], v[64:67]
	s_setprio 0
	s_barrier
	s_add_i32 s74, s74, s52
	v_lshl_add_u64 v[214:215], v[208:209], 0, s[20:21]
	s_mov_b32 m0, s74
	s_nop 0
	global_load_lds_dwordx4 v[214:215], off
	v_lshl_add_u64 v[214:215], v[208:209], 0, s[22:23]
	s_add_i32 m0, s74, 0x2000
	s_add_i32 s74, s75, s52
	global_load_lds_dwordx4 v[214:215], off
	v_lshl_add_u64 v[214:215], v[208:209], 0, s[24:25]
	s_mov_b32 m0, s74
	v_lshl_add_u64 v[208:209], v[208:209], 0, s[26:27]
	global_load_lds_dwordx4 v[214:215], off
	s_add_i32 m0, s74, 0x2000
	s_nop 0
	global_load_lds_dwordx4 v[208:209], off
	v_lshl_add_u64 v[208:209], v[212:213], 0, s[20:21]
	s_mov_b32 m0, s58
	s_nop 0
	global_load_lds_dwordx4 v[208:209], off
	v_lshl_add_u64 v[208:209], v[212:213], 0, s[22:23]
	s_mov_b32 m0, s59
	s_nop 0
	global_load_lds_dwordx4 v[208:209], off
	ds_read_b128 v[176:179], v143 offset:49152
	ds_read_b128 v[180:183], v143 offset:50176
	ds_read_b128 v[184:187], v143 offset:51200
	ds_read_b128 v[188:191], v143 offset:52224
	ds_read_b128 v[192:195], v143 offset:53248
	ds_read_b128 v[196:199], v143 offset:54272
	ds_read_b128 v[200:203], v143 offset:55296
	ds_read_b128 v[204:207], v143 offset:56320
	s_waitcnt vmcnt(8)
	s_waitcnt lgkmcnt(0)
	s_barrier
	s_setprio 1
	s_waitcnt lgkmcnt(0)
	v_mfma_f32_16x16x32_bf16 v[60:63], v[144:147], v[176:179], v[60:63]
	v_mfma_f32_16x16x32_bf16 v[56:59], v[152:155], v[176:179], v[56:59]
	v_mfma_f32_16x16x32_bf16 v[52:55], v[144:147], v[184:187], v[52:55]
	v_mfma_f32_16x16x32_bf16 v[48:51], v[152:155], v[184:187], v[48:51]
	v_mfma_f32_16x16x32_bf16 v[36:39], v[144:147], v[192:195], v[36:39]
	v_mfma_f32_16x16x32_bf16 v[32:35], v[152:155], v[192:195], v[32:35]
	v_mfma_f32_16x16x32_bf16 v[20:23], v[144:147], v[200:203], v[20:23]
	v_mfma_f32_16x16x32_bf16 v[16:19], v[152:155], v[200:203], v[16:19]
	v_mfma_f32_16x16x32_bf16 v[60:63], v[148:151], v[180:183], v[60:63]
	v_mfma_f32_16x16x32_bf16 v[56:59], v[156:159], v[180:183], v[56:59]
	v_mfma_f32_16x16x32_bf16 v[52:55], v[148:151], v[188:191], v[52:55]
	v_mfma_f32_16x16x32_bf16 v[48:51], v[156:159], v[188:191], v[48:51]
	v_mfma_f32_16x16x32_bf16 v[36:39], v[148:151], v[196:199], v[36:39]
	v_mfma_f32_16x16x32_bf16 v[32:35], v[156:159], v[196:199], v[32:35]
	v_mfma_f32_16x16x32_bf16 v[20:23], v[148:151], v[204:207], v[20:23]
	v_mfma_f32_16x16x32_bf16 v[16:19], v[156:159], v[204:207], v[16:19]
	s_setprio 0
	s_setprio 1
	v_mfma_f32_16x16x32_bf16 v[44:47], v[160:163], v[176:179], v[44:47]
	v_mfma_f32_16x16x32_bf16 v[40:43], v[168:171], v[176:179], v[40:43]
	v_mfma_f32_16x16x32_bf16 v[28:31], v[160:163], v[184:187], v[28:31]
	v_mfma_f32_16x16x32_bf16 v[24:27], v[168:171], v[184:187], v[24:27]
	v_mfma_f32_16x16x32_bf16 v[12:15], v[160:163], v[192:195], v[12:15]
	v_mfma_f32_16x16x32_bf16 v[8:11], v[168:171], v[192:195], v[8:11]
	v_mfma_f32_16x16x32_bf16 v[4:7], v[160:163], v[200:203], v[4:7]
	v_mfma_f32_16x16x32_bf16 v[0:3], v[168:171], v[200:203], v[0:3]
	v_mfma_f32_16x16x32_bf16 v[44:47], v[164:167], v[180:183], v[44:47]
	v_mfma_f32_16x16x32_bf16 v[40:43], v[172:175], v[180:183], v[40:43]
	v_mfma_f32_16x16x32_bf16 v[28:31], v[164:167], v[188:191], v[28:31]
	v_mfma_f32_16x16x32_bf16 v[24:27], v[172:175], v[188:191], v[24:27]
	v_mfma_f32_16x16x32_bf16 v[12:15], v[164:167], v[196:199], v[12:15]
	v_mfma_f32_16x16x32_bf16 v[8:11], v[172:175], v[196:199], v[8:11]
	v_mfma_f32_16x16x32_bf16 v[4:7], v[164:167], v[204:207], v[4:7]
	v_mfma_f32_16x16x32_bf16 v[0:3], v[172:175], v[204:207], v[0:3]
	s_setprio 0
	s_barrier
	s_cmp_gt_u32 s73, 41
	s_cbranch_scc0 .LBB0_255
	s_and_b64 vcc, exec, s[28:29]
	s_cbranch_vccz .LBB0_258
	s_barrier

.LBB0_969:
	s_ashr_i32 s23, s22, 31
	s_lshl_b64 s[24:25], s[22:23], 19
	s_add_u32 s24, s41, s24
	s_addc_u32 s25, s42, s25
	s_ashr_i32 s21, s20, 31
	s_lshl_b64 s[26:27], s[20:21], 19
	s_add_u32 s26, s43, s26
	s_mov_b32 s38, 0
	s_addc_u32 s27, s44, s27
	s_ashr_i32 s39, s38, 31
	s_lshl_b64 s[68:69], s[38:39], 7
	s_add_u32 s70, s68, 0x100
	s_addc_u32 s71, s69, 0
	s_add_u32 s38, s34, s70
	ds_read_b128 v[0:3], v140
	ds_read_b128 v[4:7], v140 offset:1024
	ds_read_b128 v[8:11], v140 offset:2048
	ds_read_b128 v[12:15], v140 offset:3072
	ds_read_b128 v[16:19], v141
	ds_read_b128 v[20:23], v141 offset:1024
	ds_read_b128 v[24:27], v141 offset:2048
	ds_read_b128 v[28:31], v141 offset:3072
	s_addc_u32 s39, s35, s71
	s_and_b64 s[66:67], s[36:37], exec
	s_cselect_b32 s23, s27, s31
	s_cselect_b32 s66, s26, s30
	s_add_u32 s70, s30, s70
	s_addc_u32 s71, s31, s71
	s_add_u32 s68, s34, s68
	s_mov_b32 s21, 0
	s_addc_u32 s69, s35, s69
	v_lshl_add_u64 v[64:65], s[68:69], 0, v[130:131]
	s_mov_b32 m0, s59
	v_lshl_add_u64 v[66:67], v[64:65], 0, s[14:15]
	ds_read_b128 v[32:35], v142
	ds_read_b128 v[36:39], v142 offset:1024
	ds_read_b128 v[40:43], v142 offset:2048
	ds_read_b128 v[44:47], v142 offset:3072
	ds_read_b128 v[48:51], v142 offset:4096
	ds_read_b128 v[52:55], v142 offset:5120
	ds_read_b128 v[56:59], v142 offset:6144
	ds_read_b128 v[60:63], v142 offset:7168
	global_load_lds_dwordx4 v[66:67], off
	v_lshl_add_u64 v[64:65], v[64:65], 0, s[16:17]
	s_mov_b32 m0, s60
	s_and_b64 s[68:69], s[36:37], exec
	global_load_lds_dwordx4 v[64:65], off
	s_waitcnt vmcnt(16)
	s_waitcnt lgkmcnt(0)
	s_cselect_b32 s67, s25, s35
	s_cselect_b32 s68, s24, s34
	s_barrier
	s_setprio 1
	s_waitcnt lgkmcnt(0)
	v_mfma_f32_16x16x32_bf16 v[64:67], v[0:3], v[32:35], 0
	v_mfma_f32_16x16x32_bf16 v[68:71], v[8:11], v[32:35], 0
	v_mfma_f32_16x16x32_bf16 v[72:75], v[0:3], v[40:43], 0
	v_mfma_f32_16x16x32_bf16 v[76:79], v[8:11], v[40:43], 0
	v_mfma_f32_16x16x32_bf16 v[80:83], v[0:3], v[48:51], 0
	v_mfma_f32_16x16x32_bf16 v[84:87], v[8:11], v[48:51], 0
	v_mfma_f32_16x16x32_bf16 v[88:91], v[0:3], v[56:59], 0
	v_mfma_f32_16x16x32_bf16 v[92:95], v[8:11], v[56:59], 0
	v_mfma_f32_16x16x32_bf16 v[64:67], v[4:7], v[36:39], v[64:67]
	v_mfma_f32_16x16x32_bf16 v[68:71], v[12:15], v[36:39], v[68:71]
	v_mfma_f32_16x16x32_bf16 v[72:75], v[4:7], v[44:47], v[72:75]
	v_mfma_f32_16x16x32_bf16 v[76:79], v[12:15], v[44:47], v[76:79]
	v_mfma_f32_16x16x32_bf16 v[80:83], v[4:7], v[52:55], v[80:83]
	v_mfma_f32_16x16x32_bf16 v[84:87], v[12:15], v[52:55], v[84:87]
	v_mfma_f32_16x16x32_bf16 v[88:91], v[4:7], v[60:63], v[88:91]
	v_mfma_f32_16x16x32_bf16 v[100:103], v[12:15], v[60:63], v[92:95]
	s_setprio 0
	s_setprio 1
	v_mfma_f32_16x16x32_bf16 v[92:95], v[16:19], v[32:35], 0
	v_mfma_f32_16x16x32_bf16 v[32:35], v[24:27], v[32:35], 0
	v_mfma_f32_16x16x32_bf16 v[104:107], v[20:23], v[36:39], v[92:95]
	v_mfma_f32_16x16x32_bf16 v[32:35], v[28:31], v[36:39], v[32:35]
	v_mfma_f32_16x16x32_bf16 v[36:39], v[16:19], v[40:43], 0
	v_mfma_f32_16x16x32_bf16 v[40:43], v[24:27], v[40:43], 0
	v_mfma_f32_16x16x32_bf16 v[36:39], v[20:23], v[44:47], v[36:39]
	v_mfma_f32_16x16x32_bf16 v[40:43], v[28:31], v[44:47], v[40:43]
	v_mfma_f32_16x16x32_bf16 v[44:47], v[16:19], v[48:51], 0
	v_mfma_f32_16x16x32_bf16 v[48:51], v[24:27], v[48:51], 0
	v_mfma_f32_16x16x32_bf16 v[44:47], v[20:23], v[52:55], v[44:47]
	v_mfma_f32_16x16x32_bf16 v[48:51], v[28:31], v[52:55], v[48:51]
	v_mfma_f32_16x16x32_bf16 v[52:55], v[16:19], v[56:59], 0
	v_mfma_f32_16x16x32_bf16 v[56:59], v[24:27], v[56:59], 0
	v_mfma_f32_16x16x32_bf16 v[52:55], v[20:23], v[60:63], v[52:55]
	v_mfma_f32_16x16x32_bf16 v[56:59], v[28:31], v[60:63], v[56:59]
	s_setprio 0
	s_barrier
	s_mov_b32 m0, s61
	v_lshl_add_u64 v[208:209], s[70:71], 0, v[128:129]
	global_load_lds_dwordx4 v[208:209], off
	v_lshl_add_u64 v[136:137], v[208:209], 0, s[0:1]
	s_mov_b32 m0, s62
	v_lshl_add_u64 v[248:249], s[38:39], 0, v[130:131]
	global_load_lds_dwordx4 v[136:137], off
	v_lshl_add_u64 v[136:137], v[208:209], 0, s[2:3]
	s_mov_b32 m0, s63
	s_nop 0
	global_load_lds_dwordx4 v[136:137], off
	v_lshl_add_u64 v[136:137], v[208:209], 0, s[4:5]
	s_mov_b32 m0, s64
	s_nop 0
	global_load_lds_dwordx4 v[136:137], off
	s_mov_b32 m0, s48
	v_lshl_add_u64 v[136:137], v[248:249], 0, s[0:1]
	global_load_lds_dwordx4 v[248:249], off
	s_mov_b32 m0, s49
	s_nop 0
	global_load_lds_dwordx4 v[136:137], off
	ds_read_b128 v[60:63], v142 offset:16384
	ds_read_b128 v[92:95], v142 offset:17408
	ds_read_b128 v[96:99], v142 offset:18432
	ds_read_b128 v[108:111], v142 offset:19456
	ds_read_b128 v[112:115], v142 offset:20480
	ds_read_b128 v[116:119], v142 offset:21504
	ds_read_b128 v[120:123], v142 offset:22528
	ds_read_b128 v[124:127], v142 offset:23552
	s_waitcnt vmcnt(16)
	s_waitcnt lgkmcnt(0)
	s_barrier
	s_setprio 1
	s_waitcnt lgkmcnt(0)
	v_mfma_f32_16x16x32_bf16 v[144:147], v[0:3], v[60:63], 0
	v_mfma_f32_16x16x32_bf16 v[152:155], v[0:3], v[96:99], 0
	v_mfma_f32_16x16x32_bf16 v[160:163], v[0:3], v[112:115], 0
	v_mfma_f32_16x16x32_bf16 v[0:3], v[0:3], v[120:123], 0
	v_mfma_f32_16x16x32_bf16 v[144:147], v[4:7], v[92:95], v[144:147]
	v_mfma_f32_16x16x32_bf16 v[152:155], v[4:7], v[108:111], v[152:155]
	v_mfma_f32_16x16x32_bf16 v[160:163], v[4:7], v[116:119], v[160:163]
	v_mfma_f32_16x16x32_bf16 v[0:3], v[4:7], v[124:127], v[0:3]
	v_mfma_f32_16x16x32_bf16 v[4:7], v[8:11], v[120:123], 0
	v_mfma_f32_16x16x32_bf16 v[148:151], v[8:11], v[60:63], 0
	v_mfma_f32_16x16x32_bf16 v[156:159], v[8:11], v[96:99], 0
	v_mfma_f32_16x16x32_bf16 v[164:167], v[8:11], v[112:115], 0
	v_mfma_f32_16x16x32_bf16 v[4:7], v[12:15], v[124:127], v[4:7]
	v_mfma_f32_16x16x32_bf16 v[148:151], v[12:15], v[92:95], v[148:151]
	v_mfma_f32_16x16x32_bf16 v[156:159], v[12:15], v[108:111], v[156:159]
	v_mfma_f32_16x16x32_bf16 v[164:167], v[12:15], v[116:119], v[164:167]
	s_setprio 0
	s_setprio 1
	v_mfma_f32_16x16x32_bf16 v[12:15], v[24:27], v[60:63], 0
	v_mfma_f32_16x16x32_bf16 v[172:175], v[28:31], v[92:95], v[12:15]
	v_mfma_f32_16x16x32_bf16 v[12:15], v[16:19], v[96:99], 0
	v_mfma_f32_16x16x32_bf16 v[176:179], v[20:23], v[108:111], v[12:15]
	v_mfma_f32_16x16x32_bf16 v[12:15], v[24:27], v[96:99], 0
	v_mfma_f32_16x16x32_bf16 v[180:183], v[28:31], v[108:111], v[12:15]
	v_mfma_f32_16x16x32_bf16 v[12:15], v[16:19], v[112:115], 0
	v_mfma_f32_16x16x32_bf16 v[184:187], v[20:23], v[116:119], v[12:15]
	v_mfma_f32_16x16x32_bf16 v[12:15], v[24:27], v[112:115], 0
	v_mfma_f32_16x16x32_bf16 v[8:11], v[16:19], v[60:63], 0
	v_mfma_f32_16x16x32_bf16 v[188:191], v[28:31], v[116:119], v[12:15]
	v_mfma_f32_16x16x32_bf16 v[12:15], v[16:19], v[120:123], 0
	v_mfma_f32_16x16x32_bf16 v[8:11], v[20:23], v[92:95], v[8:11]
	v_mfma_f32_16x16x32_bf16 v[192:195], v[20:23], v[124:127], v[12:15]
	v_mfma_f32_16x16x32_bf16 v[12:15], v[24:27], v[120:123], 0
	v_mfma_f32_16x16x32_bf16 v[196:199], v[28:31], v[124:127], v[12:15]
	s_setprio 0
	s_barrier
	s_add_i32 s71, 0, 0x1c000
	v_add_u32_e32 v136, s71, v139
	s_nop 2
	s_mov_b32 m0, s50
	v_lshl_add_u64 v[92:93], v[248:249], 0, s[2:3]
	global_load_lds_dwordx4 v[92:93], off
	v_lshl_add_u64 v[92:93], v[248:249], 0, s[4:5]
	s_mov_b32 m0, s51
	s_nop 0
	global_load_lds_dwordx4 v[92:93], off
	ds_read_b128 v[12:15], v143
	ds_read_b128 v[20:23], v143 offset:1024
	ds_read_b128 v[24:27], v143 offset:2048
	ds_read_b128 v[200:203], v143 offset:3072
	ds_read_b128 v[204:207], v136
	ds_read_b128 v[212:215], v136 offset:1024
	ds_read_b128 v[216:219], v136 offset:2048
	ds_read_b128 v[220:223], v136 offset:3072
	ds_read_b128 v[16:19], v142 offset:32768
	ds_read_b128 v[28:31], v142 offset:33792
	ds_read_b128 v[60:63], v142 offset:34816
	ds_read_b128 v[224:227], v142 offset:35840
	ds_read_b128 v[228:231], v142 offset:36864
	ds_read_b128 v[232:235], v142 offset:37888
	ds_read_b128 v[236:239], v142 offset:38912
	ds_read_b128 v[240:243], v142 offset:39936
	s_waitcnt vmcnt(8)
	s_waitcnt lgkmcnt(0)
	s_barrier
	s_setprio 1
	s_waitcnt lgkmcnt(0)
	v_mfma_f32_16x16x32_bf16 v[64:67], v[12:15], v[16:19], v[64:67]
	v_mfma_f32_16x16x32_bf16 v[124:127], v[20:23], v[28:31], v[64:67]
	v_mfma_f32_16x16x32_bf16 v[64:67], v[24:27], v[16:19], v[68:71]
	v_mfma_f32_16x16x32_bf16 v[112:115], v[200:203], v[28:31], v[64:67]
	v_mfma_f32_16x16x32_bf16 v[64:67], v[12:15], v[60:63], v[72:75]
	v_mfma_f32_16x16x32_bf16 v[108:111], v[20:23], v[224:227], v[64:67]
	v_mfma_f32_16x16x32_bf16 v[64:67], v[24:27], v[60:63], v[76:79]
	v_mfma_f32_16x16x32_bf16 v[96:99], v[200:203], v[224:227], v[64:67]
	v_mfma_f32_16x16x32_bf16 v[64:67], v[12:15], v[228:231], v[80:83]
	v_mfma_f32_16x16x32_bf16 v[92:95], v[20:23], v[232:235], v[64:67]
	v_mfma_f32_16x16x32_bf16 v[64:67], v[24:27], v[228:231], v[84:87]
	v_mfma_f32_16x16x32_bf16 v[80:83], v[200:203], v[232:235], v[64:67]
	v_mfma_f32_16x16x32_bf16 v[64:67], v[12:15], v[236:239], v[88:91]
	v_mfma_f32_16x16x32_bf16 v[76:79], v[20:23], v[240:243], v[64:67]
	v_mfma_f32_16x16x32_bf16 v[64:67], v[24:27], v[236:239], v[100:103]
	v_mfma_f32_16x16x32_bf16 v[64:67], v[200:203], v[240:243], v[64:67]
	s_setprio 0
	s_setprio 1
	v_mfma_f32_16x16x32_bf16 v[68:71], v[204:207], v[16:19], v[104:107]
	v_mfma_f32_16x16x32_bf16 v[16:19], v[216:219], v[16:19], v[32:35]
	v_mfma_f32_16x16x32_bf16 v[116:119], v[220:223], v[28:31], v[16:19]
	v_mfma_f32_16x16x32_bf16 v[16:19], v[204:207], v[60:63], v[36:39]
	v_mfma_f32_16x16x32_bf16 v[104:107], v[212:215], v[224:227], v[16:19]
	v_mfma_f32_16x16x32_bf16 v[16:19], v[216:219], v[60:63], v[40:43]
	v_mfma_f32_16x16x32_bf16 v[100:103], v[220:223], v[224:227], v[16:19]
	v_mfma_f32_16x16x32_bf16 v[16:19], v[204:207], v[228:231], v[44:47]
	v_mfma_f32_16x16x32_bf16 v[88:91], v[212:215], v[232:235], v[16:19]
	v_mfma_f32_16x16x32_bf16 v[16:19], v[216:219], v[228:231], v[48:51]
	v_mfma_f32_16x16x32_bf16 v[84:87], v[220:223], v[232:235], v[16:19]
	v_mfma_f32_16x16x32_bf16 v[16:19], v[204:207], v[236:239], v[52:55]
	v_mfma_f32_16x16x32_bf16 v[72:75], v[212:215], v[240:243], v[16:19]
	v_mfma_f32_16x16x32_bf16 v[16:19], v[216:219], v[236:239], v[56:59]
	v_mfma_f32_16x16x32_bf16 v[120:123], v[212:215], v[28:31], v[68:71]
	v_mfma_f32_16x16x32_bf16 v[68:71], v[220:223], v[240:243], v[16:19]
	s_setprio 0
	s_barrier
	s_add_i32 s69, s65, s45
	s_nop 2
	v_lshl_add_u64 v[16:17], v[208:209], 0, s[10:11]
	s_mov_b32 m0, s69
	s_add_i32 s70, s69, 0x2000
	global_load_lds_dwordx4 v[16:17], off
	v_lshl_add_u64 v[16:17], v[208:209], 0, s[12:13]
	s_mov_b32 m0, s70
	s_add_i32 s71, s71, s45
	global_load_lds_dwordx4 v[16:17], off
	v_lshl_add_u64 v[16:17], v[208:209], 0, s[14:15]
	s_mov_b32 m0, s71
	s_add_i32 s72, s71, 0x2000
	global_load_lds_dwordx4 v[16:17], off
	v_lshl_add_u64 v[16:17], v[208:209], 0, s[16:17]
	s_mov_b32 m0, s72
	s_nop 0
	global_load_lds_dwordx4 v[16:17], off
	v_lshl_add_u64 v[16:17], v[248:249], 0, s[10:11]
	s_mov_b32 m0, s53
	s_nop 0
	global_load_lds_dwordx4 v[16:17], off
	v_lshl_add_u64 v[16:17], v[248:249], 0, s[12:13]
	s_mov_b32 m0, s54
	s_nop 0
	global_load_lds_dwordx4 v[16:17], off
	ds_read_b128 v[36:39], v142 offset:49152
	ds_read_b128 v[40:43], v142 offset:50176
	ds_read_b128 v[224:227], v142 offset:51200
	ds_read_b128 v[228:231], v142 offset:52224
	ds_read_b128 v[232:235], v142 offset:53248
	ds_read_b128 v[236:239], v142 offset:54272
	ds_read_b128 v[240:243], v142 offset:55296
	ds_read_b128 v[244:247], v142 offset:56320
	s_waitcnt vmcnt(8)
	s_waitcnt lgkmcnt(0)
	s_barrier
	s_setprio 1
	s_waitcnt lgkmcnt(0)
	v_mfma_f32_16x16x32_bf16 v[16:19], v[12:15], v[36:39], v[144:147]
	v_mfma_f32_16x16x32_bf16 v[60:63], v[20:23], v[40:43], v[16:19]
	v_mfma_f32_16x16x32_bf16 v[16:19], v[24:27], v[36:39], v[148:151]
	v_mfma_f32_16x16x32_bf16 v[48:51], v[200:203], v[40:43], v[16:19]
	v_mfma_f32_16x16x32_bf16 v[16:19], v[12:15], v[224:227], v[152:155]
	v_mfma_f32_16x16x32_bf16 v[44:47], v[20:23], v[228:231], v[16:19]
	v_mfma_f32_16x16x32_bf16 v[16:19], v[24:27], v[224:227], v[156:159]
	v_mfma_f32_16x16x32_bf16 v[32:35], v[200:203], v[228:231], v[16:19]
	v_mfma_f32_16x16x32_bf16 v[16:19], v[12:15], v[232:235], v[160:163]
	v_mfma_f32_16x16x32_bf16 v[0:3], v[12:15], v[240:243], v[0:3]
	v_mfma_f32_16x16x32_bf16 v[28:31], v[20:23], v[236:239], v[16:19]
	v_mfma_f32_16x16x32_bf16 v[16:19], v[24:27], v[232:235], v[164:167]
	v_mfma_f32_16x16x32_bf16 v[12:15], v[20:23], v[244:247], v[0:3]
	v_mfma_f32_16x16x32_bf16 v[0:3], v[24:27], v[240:243], v[4:7]
	v_mfma_f32_16x16x32_bf16 v[16:19], v[200:203], v[236:239], v[16:19]
	v_mfma_f32_16x16x32_bf16 v[0:3], v[200:203], v[244:247], v[0:3]
	s_setprio 0
	s_setprio 1
	v_mfma_f32_16x16x32_bf16 v[4:7], v[204:207], v[36:39], v[8:11]
	v_mfma_f32_16x16x32_bf16 v[56:59], v[212:215], v[40:43], v[4:7]
	v_mfma_f32_16x16x32_bf16 v[4:7], v[216:219], v[36:39], v[172:175]
	v_mfma_f32_16x16x32_bf16 v[52:55], v[220:223], v[40:43], v[4:7]
	v_mfma_f32_16x16x32_bf16 v[4:7], v[204:207], v[224:227], v[176:179]
	v_mfma_f32_16x16x32_bf16 v[40:43], v[212:215], v[228:231], v[4:7]
	v_mfma_f32_16x16x32_bf16 v[4:7], v[216:219], v[224:227], v[180:183]
	v_mfma_f32_16x16x32_bf16 v[36:39], v[220:223], v[228:231], v[4:7]
	v_mfma_f32_16x16x32_bf16 v[4:7], v[204:207], v[232:235], v[184:187]
	v_mfma_f32_16x16x32_bf16 v[24:27], v[212:215], v[236:239], v[4:7]
	v_mfma_f32_16x16x32_bf16 v[4:7], v[216:219], v[232:235], v[188:191]
	v_mfma_f32_16x16x32_bf16 v[20:23], v[220:223], v[236:239], v[4:7]
	v_mfma_f32_16x16x32_bf16 v[4:7], v[204:207], v[240:243], v[192:195]
	v_mfma_f32_16x16x32_bf16 v[8:11], v[212:215], v[244:247], v[4:7]
	v_mfma_f32_16x16x32_bf16 v[4:7], v[216:219], v[240:243], v[196:199]
	v_mfma_f32_16x16x32_bf16 v[4:7], v[220:223], v[244:247], v[4:7]
	s_setprio 0
	s_barrier
.LBB0_970:
	s_add_i32 s21, s21, 2
	s_mov_b32 s38, s21
	s_ashr_i32 s39, s38, 31
	s_lshl_b64 s[74:75], s[38:39], 7
	s_add_u32 s39, s74, 0x100
	s_addc_u32 s73, s75, 0
	s_add_u32 s76, s34, s39
	s_addc_u32 s77, s35, s73
	s_add_u32 s78, s30, s39
	s_addc_u32 s73, s31, s73
	s_cmp_eq_u32 s38, 14
	s_cselect_b32 s39, s67, s77
	s_cselect_b32 s38, s68, s76
	s_cselect_b32 s77, s23, s73
	s_cselect_b32 s76, s66, s78
	s_add_u32 s74, s34, s74
	s_addc_u32 s75, s35, s75
	v_lshl_add_u64 v[208:209], s[74:75], 0, v[130:131]
	s_mov_b32 m0, s59
	v_lshl_add_u64 v[216:217], v[208:209], 0, s[14:15]
	global_load_lds_dwordx4 v[216:217], off
	v_lshl_add_u64 v[208:209], v[208:209], 0, s[16:17]
	s_mov_b32 m0, s60
	s_nop 0
	global_load_lds_dwordx4 v[208:209], off
	ds_read_b128 v[144:147], v140
	ds_read_b128 v[148:151], v140 offset:1024
	ds_read_b128 v[152:155], v140 offset:2048
	ds_read_b128 v[156:159], v140 offset:3072
	ds_read_b128 v[160:163], v141
	ds_read_b128 v[164:167], v141 offset:1024
	ds_read_b128 v[172:175], v141 offset:2048
	ds_read_b128 v[176:179], v141 offset:3072
	ds_read_b128 v[180:183], v142
	ds_read_b128 v[184:187], v142 offset:1024
	ds_read_b128 v[188:191], v142 offset:2048
	ds_read_b128 v[192:195], v142 offset:3072
	ds_read_b128 v[196:199], v142 offset:4096
	ds_read_b128 v[200:203], v142 offset:5120
	ds_read_b128 v[204:207], v142 offset:6144
	ds_read_b128 v[212:215], v142 offset:7168
	s_waitcnt vmcnt(8)
	s_waitcnt lgkmcnt(0)
	s_barrier
	s_setprio 1
	s_waitcnt lgkmcnt(0)
	v_mfma_f32_16x16x32_bf16 v[124:127], v[144:147], v[180:183], v[124:127]
	v_mfma_f32_16x16x32_bf16 v[112:115], v[152:155], v[180:183], v[112:115]
	v_mfma_f32_16x16x32_bf16 v[108:111], v[144:147], v[188:191], v[108:111]
	v_mfma_f32_16x16x32_bf16 v[96:99], v[152:155], v[188:191], v[96:99]
	v_mfma_f32_16x16x32_bf16 v[92:95], v[144:147], v[196:199], v[92:95]
	v_mfma_f32_16x16x32_bf16 v[80:83], v[152:155], v[196:199], v[80:83]
	v_mfma_f32_16x16x32_bf16 v[76:79], v[144:147], v[204:207], v[76:79]
	v_mfma_f32_16x16x32_bf16 v[64:67], v[152:155], v[204:207], v[64:67]
	v_mfma_f32_16x16x32_bf16 v[124:127], v[148:151], v[184:187], v[124:127]
	v_mfma_f32_16x16x32_bf16 v[112:115], v[156:159], v[184:187], v[112:115]
	v_mfma_f32_16x16x32_bf16 v[108:111], v[148:151], v[192:195], v[108:111]
	v_mfma_f32_16x16x32_bf16 v[96:99], v[156:159], v[192:195], v[96:99]
	v_mfma_f32_16x16x32_bf16 v[92:95], v[148:151], v[200:203], v[92:95]
	v_mfma_f32_16x16x32_bf16 v[80:83], v[156:159], v[200:203], v[80:83]
	v_mfma_f32_16x16x32_bf16 v[76:79], v[148:151], v[212:215], v[76:79]
	v_mfma_f32_16x16x32_bf16 v[64:67], v[156:159], v[212:215], v[64:67]
	s_setprio 0
	s_setprio 1
	v_mfma_f32_16x16x32_bf16 v[120:123], v[160:163], v[180:183], v[120:123]
	v_mfma_f32_16x16x32_bf16 v[116:119], v[172:175], v[180:183], v[116:119]
	v_mfma_f32_16x16x32_bf16 v[104:107], v[160:163], v[188:191], v[104:107]
	v_mfma_f32_16x16x32_bf16 v[100:103], v[172:175], v[188:191], v[100:103]
	v_mfma_f32_16x16x32_bf16 v[88:91], v[160:163], v[196:199], v[88:91]
	v_mfma_f32_16x16x32_bf16 v[84:87], v[172:175], v[196:199], v[84:87]
	v_mfma_f32_16x16x32_bf16 v[72:75], v[160:163], v[204:207], v[72:75]
	v_mfma_f32_16x16x32_bf16 v[68:71], v[172:175], v[204:207], v[68:71]
	v_mfma_f32_16x16x32_bf16 v[120:123], v[164:167], v[184:187], v[120:123]
	v_mfma_f32_16x16x32_bf16 v[116:119], v[176:179], v[184:187], v[116:119]
	v_mfma_f32_16x16x32_bf16 v[104:107], v[164:167], v[192:195], v[104:107]
	v_mfma_f32_16x16x32_bf16 v[100:103], v[176:179], v[192:195], v[100:103]
	v_mfma_f32_16x16x32_bf16 v[88:91], v[164:167], v[200:203], v[88:91]
	v_mfma_f32_16x16x32_bf16 v[84:87], v[176:179], v[200:203], v[84:87]
	v_mfma_f32_16x16x32_bf16 v[72:75], v[164:167], v[212:215], v[72:75]
	v_mfma_f32_16x16x32_bf16 v[68:71], v[176:179], v[212:215], v[68:71]
	s_setprio 0
	s_barrier
	s_mov_b32 m0, s61
	v_lshl_add_u64 v[208:209], s[76:77], 0, v[128:129]
	global_load_lds_dwordx4 v[208:209], off
	v_lshl_add_u64 v[216:217], v[208:209], 0, s[0:1]
	s_mov_b32 m0, s62
	s_nop 0
	global_load_lds_dwordx4 v[216:217], off
	v_lshl_add_u64 v[216:217], v[208:209], 0, s[2:3]
	s_mov_b32 m0, s63
	s_nop 0
	global_load_lds_dwordx4 v[216:217], off
	v_lshl_add_u64 v[216:217], v[208:209], 0, s[4:5]
	s_mov_b32 m0, s64
	s_nop 0
	global_load_lds_dwordx4 v[216:217], off
	v_lshl_add_u64 v[216:217], s[38:39], 0, v[130:131]
	s_mov_b32 m0, s48
	v_lshl_add_u64 v[218:219], v[216:217], 0, s[0:1]
	global_load_lds_dwordx4 v[216:217], off
	s_mov_b32 m0, s49
	s_nop 0
	global_load_lds_dwordx4 v[218:219], off
	ds_read_b128 v[180:183], v142 offset:16384
	ds_read_b128 v[184:187], v142 offset:17408
	ds_read_b128 v[188:191], v142 offset:18432
	ds_read_b128 v[192:195], v142 offset:19456
	ds_read_b128 v[196:199], v142 offset:20480
	ds_read_b128 v[200:203], v142 offset:21504
	ds_read_b128 v[204:207], v142 offset:22528
	ds_read_b128 v[212:215], v142 offset:23552
	s_waitcnt vmcnt(8)
	s_waitcnt lgkmcnt(0)
	s_barrier
	s_setprio 1
	s_waitcnt lgkmcnt(0)
	v_mfma_f32_16x16x32_bf16 v[60:63], v[144:147], v[180:183], v[60:63]
	v_mfma_f32_16x16x32_bf16 v[48:51], v[152:155], v[180:183], v[48:51]
	v_mfma_f32_16x16x32_bf16 v[44:47], v[144:147], v[188:191], v[44:47]
	v_mfma_f32_16x16x32_bf16 v[32:35], v[152:155], v[188:191], v[32:35]
	v_mfma_f32_16x16x32_bf16 v[28:31], v[144:147], v[196:199], v[28:31]
	v_mfma_f32_16x16x32_bf16 v[16:19], v[152:155], v[196:199], v[16:19]
	v_mfma_f32_16x16x32_bf16 v[12:15], v[144:147], v[204:207], v[12:15]
	v_mfma_f32_16x16x32_bf16 v[0:3], v[152:155], v[204:207], v[0:3]
	v_mfma_f32_16x16x32_bf16 v[60:63], v[148:151], v[184:187], v[60:63]
	v_mfma_f32_16x16x32_bf16 v[48:51], v[156:159], v[184:187], v[48:51]
	v_mfma_f32_16x16x32_bf16 v[44:47], v[148:151], v[192:195], v[44:47]
	v_mfma_f32_16x16x32_bf16 v[32:35], v[156:159], v[192:195], v[32:35]
	v_mfma_f32_16x16x32_bf16 v[28:31], v[148:151], v[200:203], v[28:31]
	v_mfma_f32_16x16x32_bf16 v[16:19], v[156:159], v[200:203], v[16:19]
	v_mfma_f32_16x16x32_bf16 v[12:15], v[148:151], v[212:215], v[12:15]
	v_mfma_f32_16x16x32_bf16 v[0:3], v[156:159], v[212:215], v[0:3]
	s_setprio 0
	s_setprio 1
	v_mfma_f32_16x16x32_bf16 v[56:59], v[160:163], v[180:183], v[56:59]
	v_mfma_f32_16x16x32_bf16 v[52:55], v[172:175], v[180:183], v[52:55]
	v_mfma_f32_16x16x32_bf16 v[40:43], v[160:163], v[188:191], v[40:43]
	v_mfma_f32_16x16x32_bf16 v[36:39], v[172:175], v[188:191], v[36:39]
	v_mfma_f32_16x16x32_bf16 v[24:27], v[160:163], v[196:199], v[24:27]
	v_mfma_f32_16x16x32_bf16 v[20:23], v[172:175], v[196:199], v[20:23]
	v_mfma_f32_16x16x32_bf16 v[8:11], v[160:163], v[204:207], v[8:11]
	v_mfma_f32_16x16x32_bf16 v[4:7], v[172:175], v[204:207], v[4:7]
	v_mfma_f32_16x16x32_bf16 v[56:59], v[164:167], v[184:187], v[56:59]
	v_mfma_f32_16x16x32_bf16 v[52:55], v[176:179], v[184:187], v[52:55]
	v_mfma_f32_16x16x32_bf16 v[40:43], v[164:167], v[192:195], v[40:43]
	v_mfma_f32_16x16x32_bf16 v[36:39], v[176:179], v[192:195], v[36:39]
	v_mfma_f32_16x16x32_bf16 v[24:27], v[164:167], v[200:203], v[24:27]
	v_mfma_f32_16x16x32_bf16 v[20:23], v[176:179], v[200:203], v[20:23]
	v_mfma_f32_16x16x32_bf16 v[8:11], v[164:167], v[212:215], v[8:11]
	v_mfma_f32_16x16x32_bf16 v[4:7], v[176:179], v[212:215], v[4:7]
	s_setprio 0
	s_barrier
	s_mov_b32 m0, s50
	v_lshl_add_u64 v[218:219], v[216:217], 0, s[2:3]
	global_load_lds_dwordx4 v[218:219], off
	v_lshl_add_u64 v[218:219], v[216:217], 0, s[4:5]
	s_mov_b32 m0, s51
	s_nop 0
	global_load_lds_dwordx4 v[218:219], off
	ds_read_b128 v[144:147], v143
	ds_read_b128 v[148:151], v143 offset:1024
	ds_read_b128 v[152:155], v143 offset:2048
	ds_read_b128 v[156:159], v143 offset:3072
	ds_read_b128 v[160:163], v136
	ds_read_b128 v[164:167], v136 offset:1024
	ds_read_b128 v[172:175], v136 offset:2048
	ds_read_b128 v[176:179], v136 offset:3072
	ds_read_b128 v[180:183], v142 offset:32768
	ds_read_b128 v[184:187], v142 offset:33792
	ds_read_b128 v[188:191], v142 offset:34816
	ds_read_b128 v[192:195], v142 offset:35840
	ds_read_b128 v[196:199], v142 offset:36864
	ds_read_b128 v[200:203], v142 offset:37888
	ds_read_b128 v[204:207], v142 offset:38912
	ds_read_b128 v[212:215], v142 offset:39936
	s_waitcnt vmcnt(8)
	s_waitcnt lgkmcnt(0)
	s_barrier
	s_setprio 1
	s_waitcnt lgkmcnt(0)
	v_mfma_f32_16x16x32_bf16 v[124:127], v[144:147], v[180:183], v[124:127]
	v_mfma_f32_16x16x32_bf16 v[112:115], v[152:155], v[180:183], v[112:115]
	v_mfma_f32_16x16x32_bf16 v[108:111], v[144:147], v[188:191], v[108:111]
	v_mfma_f32_16x16x32_bf16 v[96:99], v[152:155], v[188:191], v[96:99]
	v_mfma_f32_16x16x32_bf16 v[92:95], v[144:147], v[196:199], v[92:95]
	v_mfma_f32_16x16x32_bf16 v[80:83], v[152:155], v[196:199], v[80:83]
	v_mfma_f32_16x16x32_bf16 v[76:79], v[144:147], v[204:207], v[76:79]
	v_mfma_f32_16x16x32_bf16 v[64:67], v[152:155], v[204:207], v[64:67]
	v_mfma_f32_16x16x32_bf16 v[124:127], v[148:151], v[184:187], v[124:127]
	v_mfma_f32_16x16x32_bf16 v[112:115], v[156:159], v[184:187], v[112:115]
	v_mfma_f32_16x16x32_bf16 v[108:111], v[148:151], v[192:195], v[108:111]
	v_mfma_f32_16x16x32_bf16 v[96:99], v[156:159], v[192:195], v[96:99]
	v_mfma_f32_16x16x32_bf16 v[92:95], v[148:151], v[200:203], v[92:95]
	v_mfma_f32_16x16x32_bf16 v[80:83], v[156:159], v[200:203], v[80:83]
	v_mfma_f32_16x16x32_bf16 v[76:79], v[148:151], v[212:215], v[76:79]
	v_mfma_f32_16x16x32_bf16 v[64:67], v[156:159], v[212:215], v[64:67]
	s_setprio 0
	s_setprio 1
	v_mfma_f32_16x16x32_bf16 v[120:123], v[160:163], v[180:183], v[120:123]
	v_mfma_f32_16x16x32_bf16 v[116:119], v[172:175], v[180:183], v[116:119]
	v_mfma_f32_16x16x32_bf16 v[104:107], v[160:163], v[188:191], v[104:107]
	v_mfma_f32_16x16x32_bf16 v[100:103], v[172:175], v[188:191], v[100:103]
	v_mfma_f32_16x16x32_bf16 v[88:91], v[160:163], v[196:199], v[88:91]
	v_mfma_f32_16x16x32_bf16 v[84:87], v[172:175], v[196:199], v[84:87]
	v_mfma_f32_16x16x32_bf16 v[72:75], v[160:163], v[204:207], v[72:75]
	v_mfma_f32_16x16x32_bf16 v[68:71], v[172:175], v[204:207], v[68:71]
	v_mfma_f32_16x16x32_bf16 v[120:123], v[164:167], v[184:187], v[120:123]
	v_mfma_f32_16x16x32_bf16 v[116:119], v[176:179], v[184:187], v[116:119]
	v_mfma_f32_16x16x32_bf16 v[104:107], v[164:167], v[192:195], v[104:107]
	v_mfma_f32_16x16x32_bf16 v[100:103], v[176:179], v[192:195], v[100:103]
	v_mfma_f32_16x16x32_bf16 v[88:91], v[164:167], v[200:203], v[88:91]
	v_mfma_f32_16x16x32_bf16 v[84:87], v[176:179], v[200:203], v[84:87]
	v_mfma_f32_16x16x32_bf16 v[72:75], v[164:167], v[212:215], v[72:75]
	v_mfma_f32_16x16x32_bf16 v[68:71], v[176:179], v[212:215], v[68:71]
	s_setprio 0
	s_barrier
	s_mov_b32 m0, s69
	v_lshl_add_u64 v[218:219], v[208:209], 0, s[10:11]
	global_load_lds_dwordx4 v[218:219], off
	v_lshl_add_u64 v[218:219], v[208:209], 0, s[12:13]
	s_mov_b32 m0, s70
	s_nop 0
	global_load_lds_dwordx4 v[218:219], off
	v_lshl_add_u64 v[218:219], v[208:209], 0, s[14:15]
	s_mov_b32 m0, s71
	v_lshl_add_u64 v[208:209], v[208:209], 0, s[16:17]
	global_load_lds_dwordx4 v[218:219], off
	s_mov_b32 m0, s72
	s_nop 0
	global_load_lds_dwordx4 v[208:209], off
	v_lshl_add_u64 v[208:209], v[216:217], 0, s[10:11]
	s_mov_b32 m0, s53
	s_nop 0
	global_load_lds_dwordx4 v[208:209], off
	v_lshl_add_u64 v[208:209], v[216:217], 0, s[12:13]
	s_mov_b32 m0, s54
	s_nop 0
	global_load_lds_dwordx4 v[208:209], off
	ds_read_b128 v[180:183], v142 offset:49152
	ds_read_b128 v[184:187], v142 offset:50176
	ds_read_b128 v[188:191], v142 offset:51200
	ds_read_b128 v[192:195], v142 offset:52224
	ds_read_b128 v[196:199], v142 offset:53248
	ds_read_b128 v[200:203], v142 offset:54272
	ds_read_b128 v[204:207], v142 offset:55296
	ds_read_b128 v[212:215], v142 offset:56320
	s_waitcnt vmcnt(8)
	s_waitcnt lgkmcnt(0)
	s_barrier
	s_setprio 1
	s_waitcnt lgkmcnt(0)
	v_mfma_f32_16x16x32_bf16 v[60:63], v[144:147], v[180:183], v[60:63]
	v_mfma_f32_16x16x32_bf16 v[48:51], v[152:155], v[180:183], v[48:51]
	v_mfma_f32_16x16x32_bf16 v[44:47], v[144:147], v[188:191], v[44:47]
	v_mfma_f32_16x16x32_bf16 v[32:35], v[152:155], v[188:191], v[32:35]
	v_mfma_f32_16x16x32_bf16 v[28:31], v[144:147], v[196:199], v[28:31]
	v_mfma_f32_16x16x32_bf16 v[16:19], v[152:155], v[196:199], v[16:19]
	v_mfma_f32_16x16x32_bf16 v[12:15], v[144:147], v[204:207], v[12:15]
	v_mfma_f32_16x16x32_bf16 v[0:3], v[152:155], v[204:207], v[0:3]
	v_mfma_f32_16x16x32_bf16 v[60:63], v[148:151], v[184:187], v[60:63]
	v_mfma_f32_16x16x32_bf16 v[48:51], v[156:159], v[184:187], v[48:51]
	v_mfma_f32_16x16x32_bf16 v[44:47], v[148:151], v[192:195], v[44:47]
	v_mfma_f32_16x16x32_bf16 v[32:35], v[156:159], v[192:195], v[32:35]
	v_mfma_f32_16x16x32_bf16 v[28:31], v[148:151], v[200:203], v[28:31]
	v_mfma_f32_16x16x32_bf16 v[16:19], v[156:159], v[200:203], v[16:19]
	v_mfma_f32_16x16x32_bf16 v[12:15], v[148:151], v[212:215], v[12:15]
	v_mfma_f32_16x16x32_bf16 v[0:3], v[156:159], v[212:215], v[0:3]
	s_setprio 0
	s_setprio 1
	v_mfma_f32_16x16x32_bf16 v[56:59], v[160:163], v[180:183], v[56:59]
	v_mfma_f32_16x16x32_bf16 v[52:55], v[172:175], v[180:183], v[52:55]
	v_mfma_f32_16x16x32_bf16 v[40:43], v[160:163], v[188:191], v[40:43]
	v_mfma_f32_16x16x32_bf16 v[36:39], v[172:175], v[188:191], v[36:39]
	v_mfma_f32_16x16x32_bf16 v[24:27], v[160:163], v[196:199], v[24:27]
	v_mfma_f32_16x16x32_bf16 v[20:23], v[172:175], v[196:199], v[20:23]
	v_mfma_f32_16x16x32_bf16 v[8:11], v[160:163], v[204:207], v[8:11]
	v_mfma_f32_16x16x32_bf16 v[4:7], v[172:175], v[204:207], v[4:7]
	v_mfma_f32_16x16x32_bf16 v[56:59], v[164:167], v[184:187], v[56:59]
	v_mfma_f32_16x16x32_bf16 v[52:55], v[176:179], v[184:187], v[52:55]
	v_mfma_f32_16x16x32_bf16 v[40:43], v[164:167], v[192:195], v[40:43]
	v_mfma_f32_16x16x32_bf16 v[36:39], v[176:179], v[192:195], v[36:39]
	v_mfma_f32_16x16x32_bf16 v[24:27], v[164:167], v[200:203], v[24:27]
	v_mfma_f32_16x16x32_bf16 v[20:23], v[176:179], v[200:203], v[20:23]
	v_mfma_f32_16x16x32_bf16 v[8:11], v[164:167], v[212:215], v[8:11]
	v_mfma_f32_16x16x32_bf16 v[4:7], v[176:179], v[212:215], v[4:7]
	s_setprio 0
	s_barrier
	s_cmp_gt_u32 s21, 13
	s_cbranch_scc0 .LBB0_970
	s_and_b64 vcc, exec, s[18:19]
	s_cbranch_vccz .LBB0_973
	s_barrier

.LBB0_1046:
	s_add_i32 s55, s55, 2
	s_mov_b32 s56, s55
	s_ashr_i32 s57, s56, 31
	s_lshl_b64 s[58:59], s[56:57], 7
	s_add_u32 s57, s58, 0x100
	s_addc_u32 s60, s59, 0
	s_add_u32 s61, s24, s57
	s_addc_u32 s62, s25, s60
	s_add_u32 s63, s22, s57
	s_addc_u32 s60, s23, s60
	s_cmp_eq_u32 s56, 42
	s_cselect_b32 s57, s1, s62
	s_cselect_b32 s56, s0, s61
	s_cselect_b32 s61, s27, s60
	s_cselect_b32 s60, s26, s63
	v_lshl_add_u64 v[208:209], v[136:137], 0, s[58:59]
	v_lshl_add_u64 v[216:217], v[208:209], 0, s[12:13]
	s_add_i32 m0, s39, 0xc000
	s_nop 0
	global_load_lds_dwordx4 v[216:217], off
	v_lshl_add_u64 v[208:209], v[208:209], 0, s[14:15]
	s_add_i32 m0, s39, 0xe000
	s_nop 0
	global_load_lds_dwordx4 v[208:209], off
	ds_read_b128 v[144:147], v140
	ds_read_b128 v[148:151], v140 offset:1024
	ds_read_b128 v[152:155], v140 offset:2048
	ds_read_b128 v[156:159], v140 offset:3072
	ds_read_b128 v[160:163], v141
	ds_read_b128 v[164:167], v141 offset:1024
	ds_read_b128 v[172:175], v141 offset:2048
	ds_read_b128 v[176:179], v141 offset:3072
	ds_read_b128 v[180:183], v142
	ds_read_b128 v[184:187], v142 offset:1024
	ds_read_b128 v[188:191], v142 offset:2048
	ds_read_b128 v[192:195], v142 offset:3072
	ds_read_b128 v[196:199], v142 offset:4096
	ds_read_b128 v[200:203], v142 offset:5120
	ds_read_b128 v[204:207], v142 offset:6144
	ds_read_b128 v[212:215], v142 offset:7168
	s_waitcnt vmcnt(8)
	s_waitcnt lgkmcnt(0)
	s_barrier
	s_setprio 1
	s_waitcnt lgkmcnt(0)
	v_mfma_f32_16x16x32_bf16 v[124:127], v[144:147], v[180:183], v[124:127]
	v_mfma_f32_16x16x32_bf16 v[120:123], v[152:155], v[180:183], v[120:123]
	v_mfma_f32_16x16x32_bf16 v[116:119], v[144:147], v[188:191], v[116:119]
	v_mfma_f32_16x16x32_bf16 v[112:115], v[152:155], v[188:191], v[112:115]
	v_mfma_f32_16x16x32_bf16 v[100:103], v[144:147], v[196:199], v[100:103]
	v_mfma_f32_16x16x32_bf16 v[96:99], v[152:155], v[196:199], v[96:99]
	v_mfma_f32_16x16x32_bf16 v[84:87], v[144:147], v[204:207], v[84:87]
	v_mfma_f32_16x16x32_bf16 v[80:83], v[152:155], v[204:207], v[80:83]
	v_mfma_f32_16x16x32_bf16 v[124:127], v[148:151], v[184:187], v[124:127]
	v_mfma_f32_16x16x32_bf16 v[120:123], v[156:159], v[184:187], v[120:123]
	v_mfma_f32_16x16x32_bf16 v[116:119], v[148:151], v[192:195], v[116:119]
	v_mfma_f32_16x16x32_bf16 v[112:115], v[156:159], v[192:195], v[112:115]
	v_mfma_f32_16x16x32_bf16 v[100:103], v[148:151], v[200:203], v[100:103]
	v_mfma_f32_16x16x32_bf16 v[96:99], v[156:159], v[200:203], v[96:99]
	v_mfma_f32_16x16x32_bf16 v[84:87], v[148:151], v[212:215], v[84:87]
	v_mfma_f32_16x16x32_bf16 v[80:83], v[156:159], v[212:215], v[80:83]
	s_setprio 0
	s_setprio 1
	v_mfma_f32_16x16x32_bf16 v[108:111], v[160:163], v[180:183], v[108:111]
	v_mfma_f32_16x16x32_bf16 v[104:107], v[172:175], v[180:183], v[104:107]
	v_mfma_f32_16x16x32_bf16 v[92:95], v[160:163], v[188:191], v[92:95]
	v_mfma_f32_16x16x32_bf16 v[88:91], v[172:175], v[188:191], v[88:91]
	v_mfma_f32_16x16x32_bf16 v[76:79], v[160:163], v[196:199], v[76:79]
	v_mfma_f32_16x16x32_bf16 v[72:75], v[172:175], v[196:199], v[72:75]
	v_mfma_f32_16x16x32_bf16 v[68:71], v[160:163], v[204:207], v[68:71]
	v_mfma_f32_16x16x32_bf16 v[64:67], v[172:175], v[204:207], v[64:67]
	v_mfma_f32_16x16x32_bf16 v[108:111], v[164:167], v[184:187], v[108:111]
	v_mfma_f32_16x16x32_bf16 v[104:107], v[176:179], v[184:187], v[104:107]
	v_mfma_f32_16x16x32_bf16 v[92:95], v[164:167], v[192:195], v[92:95]
	v_mfma_f32_16x16x32_bf16 v[88:91], v[176:179], v[192:195], v[88:91]
	v_mfma_f32_16x16x32_bf16 v[76:79], v[164:167], v[200:203], v[76:79]
	v_mfma_f32_16x16x32_bf16 v[72:75], v[176:179], v[200:203], v[72:75]
	v_mfma_f32_16x16x32_bf16 v[68:71], v[164:167], v[212:215], v[68:71]
	v_mfma_f32_16x16x32_bf16 v[64:67], v[176:179], v[212:215], v[64:67]
	s_setprio 0
	s_barrier
	s_add_i32 s58, s49, s38
	v_lshl_add_u64 v[208:209], s[60:61], 0, v[130:131]
	s_mov_b32 m0, s58
	s_nop 0
	global_load_lds_dwordx4 v[208:209], off
	v_lshl_add_u64 v[216:217], v[208:209], 0, s[2:3]
	s_add_i32 m0, s58, 0x2000
	s_add_i32 s58, s50, s38
	global_load_lds_dwordx4 v[216:217], off
	v_lshl_add_u64 v[216:217], v[208:209], 0, s[4:5]
	s_mov_b32 m0, s58
	s_nop 0
	global_load_lds_dwordx4 v[216:217], off
	v_lshl_add_u64 v[216:217], v[208:209], 0, s[6:7]
	s_add_i32 m0, s58, 0x2000
	s_nop 0
	global_load_lds_dwordx4 v[216:217], off
	v_lshl_add_u64 v[216:217], s[56:57], 0, v[128:129]
	s_mov_b32 m0, s39
	v_lshl_add_u64 v[218:219], v[216:217], 0, s[2:3]
	global_load_lds_dwordx4 v[216:217], off
	s_mov_b32 m0, s40
	s_nop 0
	global_load_lds_dwordx4 v[218:219], off
	ds_read_b128 v[180:183], v142 offset:16384
	ds_read_b128 v[184:187], v142 offset:17408
	ds_read_b128 v[188:191], v142 offset:18432
	ds_read_b128 v[192:195], v142 offset:19456
	ds_read_b128 v[196:199], v142 offset:20480
	ds_read_b128 v[200:203], v142 offset:21504
	ds_read_b128 v[204:207], v142 offset:22528
	ds_read_b128 v[212:215], v142 offset:23552
	s_waitcnt vmcnt(8)
	s_waitcnt lgkmcnt(0)
	s_barrier
	s_setprio 1
	s_waitcnt lgkmcnt(0)
	v_mfma_f32_16x16x32_bf16 v[60:63], v[144:147], v[180:183], v[60:63]
	v_mfma_f32_16x16x32_bf16 v[56:59], v[152:155], v[180:183], v[56:59]
	v_mfma_f32_16x16x32_bf16 v[52:55], v[144:147], v[188:191], v[52:55]
	v_mfma_f32_16x16x32_bf16 v[48:51], v[152:155], v[188:191], v[48:51]
	v_mfma_f32_16x16x32_bf16 v[36:39], v[144:147], v[196:199], v[36:39]
	v_mfma_f32_16x16x32_bf16 v[32:35], v[152:155], v[196:199], v[32:35]
	v_mfma_f32_16x16x32_bf16 v[20:23], v[144:147], v[204:207], v[20:23]
	v_mfma_f32_16x16x32_bf16 v[16:19], v[152:155], v[204:207], v[16:19]
	v_mfma_f32_16x16x32_bf16 v[60:63], v[148:151], v[184:187], v[60:63]
	v_mfma_f32_16x16x32_bf16 v[56:59], v[156:159], v[184:187], v[56:59]
	v_mfma_f32_16x16x32_bf16 v[52:55], v[148:151], v[192:195], v[52:55]
	v_mfma_f32_16x16x32_bf16 v[48:51], v[156:159], v[192:195], v[48:51]
	v_mfma_f32_16x16x32_bf16 v[36:39], v[148:151], v[200:203], v[36:39]
	v_mfma_f32_16x16x32_bf16 v[32:35], v[156:159], v[200:203], v[32:35]
	v_mfma_f32_16x16x32_bf16 v[20:23], v[148:151], v[212:215], v[20:23]
	v_mfma_f32_16x16x32_bf16 v[16:19], v[156:159], v[212:215], v[16:19]
	s_setprio 0
	s_setprio 1
	v_mfma_f32_16x16x32_bf16 v[44:47], v[160:163], v[180:183], v[44:47]
	v_mfma_f32_16x16x32_bf16 v[40:43], v[172:175], v[180:183], v[40:43]
	v_mfma_f32_16x16x32_bf16 v[28:31], v[160:163], v[188:191], v[28:31]
	v_mfma_f32_16x16x32_bf16 v[24:27], v[172:175], v[188:191], v[24:27]
	v_mfma_f32_16x16x32_bf16 v[12:15], v[160:163], v[196:199], v[12:15]
	v_mfma_f32_16x16x32_bf16 v[8:11], v[172:175], v[196:199], v[8:11]
	v_mfma_f32_16x16x32_bf16 v[4:7], v[160:163], v[204:207], v[4:7]
	v_mfma_f32_16x16x32_bf16 v[0:3], v[172:175], v[204:207], v[0:3]
	v_mfma_f32_16x16x32_bf16 v[44:47], v[164:167], v[184:187], v[44:47]
	v_mfma_f32_16x16x32_bf16 v[40:43], v[176:179], v[184:187], v[40:43]
	v_mfma_f32_16x16x32_bf16 v[28:31], v[164:167], v[192:195], v[28:31]
	v_mfma_f32_16x16x32_bf16 v[24:27], v[176:179], v[192:195], v[24:27]
	v_mfma_f32_16x16x32_bf16 v[12:15], v[164:167], v[200:203], v[12:15]
	v_mfma_f32_16x16x32_bf16 v[8:11], v[176:179], v[200:203], v[8:11]
	v_mfma_f32_16x16x32_bf16 v[4:7], v[164:167], v[212:215], v[4:7]
	v_mfma_f32_16x16x32_bf16 v[0:3], v[176:179], v[212:215], v[0:3]
	s_setprio 0
	s_barrier
	s_mov_b32 m0, s41
	v_lshl_add_u64 v[218:219], v[216:217], 0, s[4:5]
	global_load_lds_dwordx4 v[218:219], off
	v_lshl_add_u64 v[218:219], v[216:217], 0, s[6:7]
	s_mov_b32 m0, s42
	s_nop 0
	global_load_lds_dwordx4 v[218:219], off
	s_add_i32 s56, 0, 0x18000
	v_add_u32_e32 v143, s56, v139
	s_add_i32 s57, 0, 0x1c000
	ds_read_b128 v[144:147], v143
	ds_read_b128 v[148:151], v143 offset:1024
	ds_read_b128 v[152:155], v143 offset:2048
	ds_read_b128 v[156:159], v143 offset:3072
	v_add_u32_e32 v143, s57, v139
	ds_read_b128 v[160:163], v143
	ds_read_b128 v[164:167], v143 offset:1024
	ds_read_b128 v[172:175], v143 offset:2048
	ds_read_b128 v[176:179], v143 offset:3072
	ds_read_b128 v[180:183], v142 offset:32768
	ds_read_b128 v[184:187], v142 offset:33792
	ds_read_b128 v[188:191], v142 offset:34816
	ds_read_b128 v[192:195], v142 offset:35840
	ds_read_b128 v[196:199], v142 offset:36864
	ds_read_b128 v[200:203], v142 offset:37888
	ds_read_b128 v[204:207], v142 offset:38912
	ds_read_b128 v[212:215], v142 offset:39936
	s_nop 0
	s_waitcnt vmcnt(8)
	s_waitcnt lgkmcnt(0)
	s_barrier
	s_setprio 1
	s_waitcnt lgkmcnt(0)
	v_mfma_f32_16x16x32_bf16 v[124:127], v[144:147], v[180:183], v[124:127]
	v_mfma_f32_16x16x32_bf16 v[120:123], v[152:155], v[180:183], v[120:123]
	v_mfma_f32_16x16x32_bf16 v[116:119], v[144:147], v[188:191], v[116:119]
	v_mfma_f32_16x16x32_bf16 v[112:115], v[152:155], v[188:191], v[112:115]
	v_mfma_f32_16x16x32_bf16 v[100:103], v[144:147], v[196:199], v[100:103]
	v_mfma_f32_16x16x32_bf16 v[96:99], v[152:155], v[196:199], v[96:99]
	v_mfma_f32_16x16x32_bf16 v[84:87], v[144:147], v[204:207], v[84:87]
	v_mfma_f32_16x16x32_bf16 v[80:83], v[152:155], v[204:207], v[80:83]
	v_mfma_f32_16x16x32_bf16 v[124:127], v[148:151], v[184:187], v[124:127]
	v_mfma_f32_16x16x32_bf16 v[120:123], v[156:159], v[184:187], v[120:123]
	v_mfma_f32_16x16x32_bf16 v[116:119], v[148:151], v[192:195], v[116:119]
	v_mfma_f32_16x16x32_bf16 v[112:115], v[156:159], v[192:195], v[112:115]
	v_mfma_f32_16x16x32_bf16 v[100:103], v[148:151], v[200:203], v[100:103]
	v_mfma_f32_16x16x32_bf16 v[96:99], v[156:159], v[200:203], v[96:99]
	v_mfma_f32_16x16x32_bf16 v[84:87], v[148:151], v[212:215], v[84:87]
	v_mfma_f32_16x16x32_bf16 v[80:83], v[156:159], v[212:215], v[80:83]
	s_setprio 0
	s_setprio 1
	v_mfma_f32_16x16x32_bf16 v[108:111], v[160:163], v[180:183], v[108:111]
	v_mfma_f32_16x16x32_bf16 v[104:107], v[172:175], v[180:183], v[104:107]
	v_mfma_f32_16x16x32_bf16 v[92:95], v[160:163], v[188:191], v[92:95]
	v_mfma_f32_16x16x32_bf16 v[88:91], v[172:175], v[188:191], v[88:91]
	v_mfma_f32_16x16x32_bf16 v[76:79], v[160:163], v[196:199], v[76:79]
	v_mfma_f32_16x16x32_bf16 v[72:75], v[172:175], v[196:199], v[72:75]
	v_mfma_f32_16x16x32_bf16 v[68:71], v[160:163], v[204:207], v[68:71]
	v_mfma_f32_16x16x32_bf16 v[64:67], v[172:175], v[204:207], v[64:67]
	v_mfma_f32_16x16x32_bf16 v[108:111], v[164:167], v[184:187], v[108:111]
	v_mfma_f32_16x16x32_bf16 v[104:107], v[176:179], v[184:187], v[104:107]
	v_mfma_f32_16x16x32_bf16 v[92:95], v[164:167], v[192:195], v[92:95]
	v_mfma_f32_16x16x32_bf16 v[88:91], v[176:179], v[192:195], v[88:91]
	v_mfma_f32_16x16x32_bf16 v[76:79], v[164:167], v[200:203], v[76:79]
	v_mfma_f32_16x16x32_bf16 v[72:75], v[176:179], v[200:203], v[72:75]
	v_mfma_f32_16x16x32_bf16 v[68:71], v[164:167], v[212:215], v[68:71]
	v_mfma_f32_16x16x32_bf16 v[64:67], v[176:179], v[212:215], v[64:67]
	s_setprio 0
	s_barrier
	s_add_i32 s56, s56, s38
	v_lshl_add_u64 v[218:219], v[208:209], 0, s[12:13]
	s_mov_b32 m0, s56
	s_nop 0
	global_load_lds_dwordx4 v[218:219], off
	v_lshl_add_u64 v[218:219], v[208:209], 0, s[14:15]
	s_add_i32 m0, s56, 0x2000
	s_add_i32 s56, s57, s38
	global_load_lds_dwordx4 v[218:219], off
	v_lshl_add_u64 v[218:219], v[208:209], 0, s[16:17]
	s_mov_b32 m0, s56
	v_lshl_add_u64 v[208:209], v[208:209], 0, s[18:19]
	global_load_lds_dwordx4 v[218:219], off
	s_add_i32 m0, s56, 0x2000
	s_nop 0
	global_load_lds_dwordx4 v[208:209], off
	v_lshl_add_u64 v[208:209], v[216:217], 0, s[12:13]
	s_mov_b32 m0, s44
	s_nop 0
	global_load_lds_dwordx4 v[208:209], off
	v_lshl_add_u64 v[208:209], v[216:217], 0, s[14:15]
	s_mov_b32 m0, s45
	s_nop 0
	global_load_lds_dwordx4 v[208:209], off
	ds_read_b128 v[180:183], v142 offset:49152
	ds_read_b128 v[184:187], v142 offset:50176
	ds_read_b128 v[188:191], v142 offset:51200
	ds_read_b128 v[192:195], v142 offset:52224
	ds_read_b128 v[196:199], v142 offset:53248
	ds_read_b128 v[200:203], v142 offset:54272
	ds_read_b128 v[204:207], v142 offset:55296
	ds_read_b128 v[212:215], v142 offset:56320
	s_waitcnt vmcnt(8)
	s_waitcnt lgkmcnt(0)
	s_barrier
	s_setprio 1
	s_waitcnt lgkmcnt(0)
	v_mfma_f32_16x16x32_bf16 v[60:63], v[144:147], v[180:183], v[60:63]
	v_mfma_f32_16x16x32_bf16 v[56:59], v[152:155], v[180:183], v[56:59]
	v_mfma_f32_16x16x32_bf16 v[52:55], v[144:147], v[188:191], v[52:55]
	v_mfma_f32_16x16x32_bf16 v[48:51], v[152:155], v[188:191], v[48:51]
	v_mfma_f32_16x16x32_bf16 v[36:39], v[144:147], v[196:199], v[36:39]
	v_mfma_f32_16x16x32_bf16 v[32:35], v[152:155], v[196:199], v[32:35]
	v_mfma_f32_16x16x32_bf16 v[20:23], v[144:147], v[204:207], v[20:23]
	v_mfma_f32_16x16x32_bf16 v[16:19], v[152:155], v[204:207], v[16:19]
	v_mfma_f32_16x16x32_bf16 v[60:63], v[148:151], v[184:187], v[60:63]
	v_mfma_f32_16x16x32_bf16 v[56:59], v[156:159], v[184:187], v[56:59]
	v_mfma_f32_16x16x32_bf16 v[52:55], v[148:151], v[192:195], v[52:55]
	v_mfma_f32_16x16x32_bf16 v[48:51], v[156:159], v[192:195], v[48:51]
	v_mfma_f32_16x16x32_bf16 v[36:39], v[148:151], v[200:203], v[36:39]
	v_mfma_f32_16x16x32_bf16 v[32:35], v[156:159], v[200:203], v[32:35]
	v_mfma_f32_16x16x32_bf16 v[20:23], v[148:151], v[212:215], v[20:23]
	v_mfma_f32_16x16x32_bf16 v[16:19], v[156:159], v[212:215], v[16:19]
	s_setprio 0
	s_setprio 1
	v_mfma_f32_16x16x32_bf16 v[44:47], v[160:163], v[180:183], v[44:47]
	v_mfma_f32_16x16x32_bf16 v[40:43], v[172:175], v[180:183], v[40:43]
	v_mfma_f32_16x16x32_bf16 v[28:31], v[160:163], v[188:191], v[28:31]
	v_mfma_f32_16x16x32_bf16 v[24:27], v[172:175], v[188:191], v[24:27]
	v_mfma_f32_16x16x32_bf16 v[12:15], v[160:163], v[196:199], v[12:15]
	v_mfma_f32_16x16x32_bf16 v[8:11], v[172:175], v[196:199], v[8:11]
	v_mfma_f32_16x16x32_bf16 v[4:7], v[160:163], v[204:207], v[4:7]
	v_mfma_f32_16x16x32_bf16 v[0:3], v[172:175], v[204:207], v[0:3]
	v_mfma_f32_16x16x32_bf16 v[44:47], v[164:167], v[184:187], v[44:47]
	v_mfma_f32_16x16x32_bf16 v[40:43], v[176:179], v[184:187], v[40:43]
	v_mfma_f32_16x16x32_bf16 v[28:31], v[164:167], v[192:195], v[28:31]
	v_mfma_f32_16x16x32_bf16 v[24:27], v[176:179], v[192:195], v[24:27]
	v_mfma_f32_16x16x32_bf16 v[12:15], v[164:167], v[200:203], v[12:15]
	v_mfma_f32_16x16x32_bf16 v[8:11], v[176:179], v[200:203], v[8:11]
	v_mfma_f32_16x16x32_bf16 v[4:7], v[164:167], v[212:215], v[4:7]
	v_mfma_f32_16x16x32_bf16 v[0:3], v[176:179], v[212:215], v[0:3]
	s_setprio 0
	s_barrier
	s_cmp_gt_u32 s55, 41
	s_cbranch_scc0 .LBB0_1046
	s_and_b64 vcc, exec, s[20:21]
	s_cbranch_vccz .LBB0_1049
	s_barrier
